# NA attention: relative-position-bias loads of each query row issued right after the row's Q loads (counted waits keep them in flight)
# speedup vs baseline: 1.0222x; 1.0010x over previous
.LBB0_118:
	s_ashr_i32 s2, s63, 6
	s_ashr_i32 s56, s63, 2
	s_ashr_i32 s3, s2, 31
	s_and_b32 s58, s56, 15
	s_lshl_b64 s[2:3], s[2:3], 10
	s_add_u32 s2, s2, 0x2000
	s_addc_u32 s3, s3, 0
	s_lshl_b64 s[20:21], s[2:3], 11
	v_readlane_b32 s22, v253, 4
	v_readlane_b32 s23, v253, 5
	s_add_u32 s20, s22, s20
	s_addc_u32 s21, s23, s21
	s_lshl_b32 s26, s58, 7
	s_add_u32 s34, s20, s26
	s_addc_u32 s35, s21, 0
	s_lshl_b32 s20, s63, 2
	s_and_b32 s22, s20, 12
	v_sub_u32_e64 v0, s22, 4 clamp
	v_lshlrev_b32_e32 v1, 6, v0
	v_add_u32_e32 v2, v1, v108
	v_ashrrev_i32_e32 v3, 31, v2
	v_lshl_add_u64 v[70:71], s[34:35], 0, v[178:179]
	v_lshlrev_b64 v[2:3], 11, v[2:3]
	v_lshl_add_u64 v[2:3], v[70:71], 0, v[2:3]
	s_barrier
	global_load_dwordx4 v[12:15], v[2:3], off
	v_and_b32_e32 v1, 0x100, v1
	s_ashr_i32 s57, s56, 31
	v_add_u32_e32 v6, v1, v108
	s_movk_i32 s59, 0x90
	s_lshl_b64 s[36:37], s[56:57], 17
	v_mad_u64_u32 v[80:81], s[34:35], v6, s59, v[110:111]
	v_lshl_add_u64 v[68:69], v[138:139], 0, s[36:37]
	s_max_u32 s21, s22, 4
	s_lshl_b32 s20, s21, 6
	v_lshl_add_u32 v146, v1, 1, v109
	s_add_i32 s34, s20, 0xffffff40
	s_and_b32 s23, s34, 0x140
	s_mov_b32 s35, s27
	v_mov_b32_e32 v145, s3
	v_lshl_add_u64 v[142:143], v[112:113], 0, s[26:27]
	s_mov_b64 s[0:1], s[90:91]
	v_readlane_b32 s80, v253, 46
	v_readlane_b32 s94, v253, 60
	v_readlane_b32 s95, v253, 61
	v_lshlrev_b32_e32 v97, 2, v122
	v_lshlrev_b32_e32 v95, 2, v126
	v_lshlrev_b32_e32 v93, 2, v124
	v_lshlrev_b32_e32 v98, 2, v118
	v_lshlrev_b32_e32 v92, 2, v128
	v_lshlrev_b32_e32 v99, 2, v114
	v_lshlrev_b32_e32 v96, 2, v116
	v_lshlrev_b32_e32 v94, 2, v120
	v_readlane_b32 s81, v253, 47
	v_readlane_b32 s82, v253, 48
	v_readlane_b32 s83, v253, 49
	v_readlane_b32 s84, v253, 50
	v_readlane_b32 s85, v253, 51
	v_readlane_b32 s86, v253, 52
	v_readlane_b32 s87, v253, 53
	v_readlane_b32 s88, v253, 54
	v_readlane_b32 s89, v253, 55
	v_readlane_b32 s90, v253, 56
	v_readlane_b32 s91, v253, 57
	v_readlane_b32 s92, v253, 58
	v_readlane_b32 s93, v253, 59
	v_lshlrev_b32_e32 v2, 7, v0
	v_mov_b32_e32 v3, v179
	v_lshl_add_u64 v[2:3], v[68:69], 0, v[2:3]
	global_load_dwordx4 v[16:19], v[2:3], off
	v_add_u32_e32 v2, s34, v108
	v_ashrrev_i32_e32 v3, 31, v2
	v_lshlrev_b64 v[2:3], 11, v[2:3]
	v_lshl_add_u64 v[2:3], v[70:71], 0, v[2:3]
	global_load_dwordx4 v[20:23], v[2:3], off
	v_add_u32_e32 v1, s23, v108
	v_mad_u64_u32 v[82:83], s[36:37], v1, s59, v[110:111]
	v_lshl_add_u32 v147, s23, 1, v109
	v_lshl_add_u64 v[2:3], s[34:35], 1, v[68:69]
	global_load_dwordx4 v[24:27], v[2:3], off
	s_add_i32 s34, s20, 0xffffff80
	s_and_b32 s23, s34, 0x180
	v_add_u32_e32 v2, s34, v108
	v_ashrrev_i32_e32 v3, 31, v2
	v_lshlrev_b64 v[2:3], 11, v[2:3]
	v_lshl_add_u64 v[2:3], v[70:71], 0, v[2:3]
	global_load_dwordx4 v[28:31], v[2:3], off
	v_add_u32_e32 v1, s23, v108
	v_mad_u64_u32 v[84:85], s[36:37], v1, s59, v[110:111]
	v_lshl_add_u32 v148, s23, 1, v109
	v_lshl_add_u64 v[2:3], s[34:35], 1, v[68:69]
	global_load_dwordx4 v[32:35], v[2:3], off
	s_sub_i32 s34, s20, 64
	s_and_b32 s23, s34, 0x1c0
	v_add_u32_e32 v2, s34, v108
	v_ashrrev_i32_e32 v3, 31, v2
	v_lshlrev_b64 v[2:3], 11, v[2:3]
	v_lshl_add_u64 v[2:3], v[70:71], 0, v[2:3]
	global_load_dwordx4 v[36:39], v[2:3], off
	v_add_u32_e32 v1, s23, v108
	v_mad_u64_u32 v[86:87], s[36:37], v1, s59, v[110:111]
	v_lshl_add_u32 v149, s23, 1, v109
	s_and_b32 s23, s20, 0x100
	v_lshl_add_u64 v[2:3], s[34:35], 1, v[68:69]
	global_load_dwordx4 v[40:43], v[2:3], off
	v_add_u32_e32 v2, s20, v108
	v_ashrrev_i32_e32 v3, 31, v2
	v_lshlrev_b64 v[2:3], 11, v[2:3]
	v_lshl_add_u64 v[2:3], v[70:71], 0, v[2:3]
	global_load_dwordx4 v[44:47], v[2:3], off
	v_add_u32_e32 v1, s23, v108
	v_mad_u64_u32 v[100:101], s[34:35], v1, s59, v[110:111]
	s_lshl_b32 s34, s21, 7
	s_mov_b32 s35, s27
	v_lshl_add_u32 v150, s23, 1, v109
	s_or_b32 s21, s20, 64
	v_lshl_add_u64 v[6:7], v[68:69], 0, s[34:35]
	global_load_dwordx4 v[48:51], v[6:7], off
	v_add_u32_e32 v2, s21, v108
	v_ashrrev_i32_e32 v3, 31, v2
	v_lshlrev_b64 v[2:3], 11, v[2:3]
	v_lshl_add_u64 v[2:3], v[70:71], 0, v[2:3]
	global_load_dwordx4 v[52:55], v[2:3], off
	s_and_b32 s21, s21, 0x140
	v_add_u32_e32 v1, s21, v108
	v_mad_u64_u32 v[102:103], s[34:35], v1, s59, v[110:111]
	v_lshl_add_u32 v151, s21, 1, v109
	s_or_b32 s21, s20, 0x80
	s_or_b32 s20, s20, 0xc0
	global_load_dwordx4 v[56:59], v[6:7], off offset:128
	v_add_u32_e32 v2, s21, v108
	v_ashrrev_i32_e32 v3, 31, v2
	v_lshlrev_b64 v[2:3], 11, v[2:3]
	v_lshl_add_u64 v[2:3], v[70:71], 0, v[2:3]
	global_load_dwordx4 v[60:63], v[2:3], off
	s_and_b32 s21, s21, 0x180
	v_add_u32_e32 v1, s21, v108
	v_mad_u64_u32 v[104:105], s[34:35], v1, s59, v[110:111]
	v_lshl_add_u32 v152, s21, 1, v109
	global_load_dwordx4 v[64:67], v[6:7], off offset:256
	v_add_u32_e32 v2, s20, v108
	v_ashrrev_i32_e32 v3, 31, v2
	v_lshlrev_b64 v[2:3], 11, v[2:3]
	v_lshl_add_u64 v[2:3], v[70:71], 0, v[2:3]
	global_load_dwordx4 v[72:75], v[2:3], off
	s_and_b32 s20, s20, 0x1c0
	v_add_u32_e32 v1, s20, v108
	v_mad_u64_u32 v[106:107], s[34:35], v1, s59, v[110:111]
	v_lshl_add_u32 v153, s20, 1, v109
	s_mul_i32 s20, s58, 0x744
	s_add_u32 s36, s94, s20
	v_readfirstlane_b32 s20, v0
	s_addc_u32 s23, s95, 0
	s_add_i32 s20, s20, s61
	s_sub_i32 s21, s20, s22
	s_lshl_b32 s20, s20, 6
	s_and_b32 s35, s20, 0x100
	v_or_b32_e32 v0, s35, v115
	s_or_b32 s34, s35, 64
	s_or_b32 s33, s35, 0x80
	s_or_b32 s26, s35, 0xc0
	s_mul_i32 s20, s21, 31
	s_ashr_i32 s21, s20, 31
	s_lshl_b64 s[20:21], s[20:21], 2
	s_add_u32 s20, s36, s20
	s_addc_u32 s21, s23, s21
	global_load_dwordx4 v[76:79], v[6:7], off offset:384
	s_waitcnt vmcnt(15)
	ds_write_b128 v80, v[12:15]
	s_waitcnt vmcnt(14)
	ds_write_b128 v146, v[16:19]
	s_waitcnt vmcnt(13)
	ds_write_b128 v82, v[20:23]
	s_waitcnt vmcnt(12)
	ds_write_b128 v147, v[24:27]
	s_waitcnt vmcnt(11)
	ds_write_b128 v84, v[28:31]
	s_waitcnt vmcnt(10)
	ds_write_b128 v148, v[32:35]
	s_waitcnt vmcnt(9)
	ds_write_b128 v86, v[36:39]
	s_waitcnt vmcnt(8)
	ds_write_b128 v149, v[40:43]
	s_waitcnt vmcnt(7)
	ds_write_b128 v100, v[44:47]
	s_waitcnt vmcnt(6)
	ds_write_b128 v150, v[48:51]
	s_waitcnt vmcnt(5)
	ds_write_b128 v102, v[52:55]
	s_waitcnt vmcnt(4)
	ds_write_b128 v151, v[56:59]
	s_waitcnt vmcnt(3)
	ds_write_b128 v104, v[60:63]
	s_waitcnt vmcnt(2)
	ds_write_b128 v152, v[64:67]
	s_waitcnt vmcnt(1)
	ds_write_b128 v106, v[72:75]
	s_waitcnt vmcnt(0)
	ds_write_b128 v153, v[76:79]
	v_lshl_or_b32 v1, s22, 6, v111
	v_or_b32_e32 v144, s2, v1
	v_lshlrev_b64 v[140:141], 11, v[144:145]
	v_lshl_add_u64 v[88:89], v[142:143], 0, v[140:141]
	s_waitcnt lgkmcnt(0)
	s_barrier
	global_load_dwordx4 v[20:23], v[88:89], off
	global_load_dwordx4 v[24:27], v[88:89], off offset:64
	global_load_dword v194, v98, s[20:21] offset:868
	global_load_dword v195, v99, s[20:21] offset:868
	global_load_dword v196, v97, s[20:21] offset:868
	global_load_dword v197, v95, s[20:21] offset:868
	global_load_dword v198, v93, s[20:21] offset:868
	global_load_dword v199, v96, s[20:21] offset:868
	global_load_dword v200, v97, s[20:21] offset:992
	global_load_dword v201, v93, s[20:21] offset:992
	global_load_dword v202, v92, s[20:21] offset:868
	global_load_dword v203, v95, s[20:21] offset:992
	global_load_dword v204, v98, s[20:21] offset:992
	global_load_dword v205, v94, s[20:21] offset:868
	global_load_dword v206, v92, s[20:21] offset:992
	global_load_dword v207, v99, s[20:21] offset:1116
	global_load_dword v208, v96, s[20:21] offset:1116
	global_load_dword v209, v98, s[20:21] offset:1116
	global_load_dword v210, v94, s[20:21] offset:1116
	global_load_dword v211, v97, s[20:21] offset:1116
	global_load_dword v212, v93, s[20:21] offset:1116
	global_load_dword v213, v96, s[20:21] offset:992
	global_load_dword v226, v95, s[20:21] offset:1116
	global_load_dword v227, v92, s[20:21] offset:1116
	global_load_dword v228, v94, s[20:21] offset:992
	global_load_dword v229, v99, s[20:21] offset:1240
	global_load_dword v230, v96, s[20:21] offset:1240
	global_load_dword v231, v98, s[20:21] offset:1240
	global_load_dword v232, v94, s[20:21] offset:1240
	global_load_dword v233, v99, s[20:21] offset:992
	global_load_dword v234, v97, s[20:21] offset:1240
	global_load_dword v235, v93, s[20:21] offset:1240
	global_load_dword v236, v95, s[20:21] offset:1240
	global_load_dword v237, v92, s[20:21] offset:1240
	v_mad_u32_u24 v4, v0, s59, v117
	ds_read_b128 v[0:3], v4
	ds_read_b128 v[4:7], v4 offset:64
	s_waitcnt vmcnt(33) lgkmcnt(1)
	v_mfma_f32_16x16x32_bf16 v[0:3], v[0:3], v[20:23], 0
	s_waitcnt vmcnt(32) lgkmcnt(0)
	v_mfma_f32_16x16x32_bf16 v[28:31], v[4:7], v[24:27], v[0:3]
	s_nop 5
	v_or_b32_e32 v0, s35, v119
	v_mad_u32_u24 v4, v0, s59, v117
	ds_read_b128 v[0:3], v4
	ds_read_b128 v[4:7], v4 offset:64
	s_waitcnt lgkmcnt(1)
	v_mfma_f32_16x16x32_bf16 v[0:3], v[0:3], v[20:23], 0
	s_waitcnt lgkmcnt(0)
	v_mfma_f32_16x16x32_bf16 v[32:35], v[4:7], v[24:27], v[0:3]
	s_nop 5
	v_add_u32_e32 v0, s34, v115
	v_mad_u32_u24 v4, v0, s59, v117
	ds_read_b128 v[0:3], v4
	ds_read_b128 v[4:7], v4 offset:64
	s_waitcnt lgkmcnt(1)
	v_mfma_f32_16x16x32_bf16 v[0:3], v[0:3], v[20:23], 0
	s_waitcnt lgkmcnt(0)
	v_mfma_f32_16x16x32_bf16 v[36:39], v[4:7], v[24:27], v[0:3]
	s_nop 5
	v_add_u32_e32 v0, s34, v119
	v_mad_u32_u24 v4, v0, s59, v117
	ds_read_b128 v[0:3], v4
	ds_read_b128 v[4:7], v4 offset:64
	s_waitcnt lgkmcnt(1)
	v_mfma_f32_16x16x32_bf16 v[0:3], v[0:3], v[20:23], 0
	s_waitcnt lgkmcnt(0)
	v_mfma_f32_16x16x32_bf16 v[16:19], v[4:7], v[24:27], v[0:3]
	s_nop 5
	v_or_b32_e32 v0, s33, v115
	v_mad_u32_u24 v4, v0, s59, v117
	ds_read_b128 v[0:3], v4
	ds_read_b128 v[4:7], v4 offset:64
	s_waitcnt lgkmcnt(1)
	v_mfma_f32_16x16x32_bf16 v[0:3], v[0:3], v[20:23], 0
	s_waitcnt lgkmcnt(0)
	v_mfma_f32_16x16x32_bf16 v[12:15], v[4:7], v[24:27], v[0:3]
	s_nop 5
	v_add_u32_e32 v0, s33, v119
	v_mad_u32_u24 v4, v0, s59, v117
	ds_read_b128 v[0:3], v4
	ds_read_b128 v[4:7], v4 offset:64
	s_waitcnt lgkmcnt(1)
	v_mfma_f32_16x16x32_bf16 v[0:3], v[0:3], v[20:23], 0
	s_waitcnt lgkmcnt(0)
	v_mfma_f32_16x16x32_bf16 v[8:11], v[4:7], v[24:27], v[0:3]
	s_nop 5
	v_add_u32_e32 v0, s26, v115
	v_mad_u32_u24 v4, v0, s59, v117
	ds_read_b128 v[0:3], v4
	ds_read_b128 v[4:7], v4 offset:64
	s_waitcnt lgkmcnt(1)
	v_mfma_f32_16x16x32_bf16 v[0:3], v[0:3], v[20:23], 0
	s_waitcnt lgkmcnt(0)
	v_mfma_f32_16x16x32_bf16 v[4:7], v[4:7], v[24:27], v[0:3]
	s_nop 5
	v_add_u32_e32 v0, s26, v119
	v_mad_u32_u24 v40, v0, s59, v117
	ds_read_b128 v[0:3], v40
	ds_read_b128 v[40:43], v40 offset:64
	s_waitcnt lgkmcnt(1)
	v_mfma_f32_16x16x32_bf16 v[0:3], v[0:3], v[20:23], 0
	s_waitcnt lgkmcnt(0)
	v_mfma_f32_16x16x32_bf16 v[0:3], v[40:43], v[24:27], v[0:3]
	s_waitcnt vmcnt(0)
	v_fmamk_f32 v24, v196, 0x3fb8aa3b, v32
	v_cndmask_b32_e64 v24, v220, v24, s[46:47]
	v_fmamk_f32 v16, v200, 0x3fb8aa3b, v16
	v_fmamk_f32 v26, v197, 0x3fb8aa3b, v34
	v_cndmask_b32_e64 v27, v220, v26, s[50:51]
	v_cndmask_b32_e64 v16, v220, v16, s[46:47]
	v_fmamk_f32 v17, v201, 0x3fb8aa3b, v17
	v_fmamk_f32 v22, v194, 0x3fb8aa3b, v30
	v_cndmask_b32_e64 v23, v220, v22, s[42:43]
	v_cndmask_b32_e64 v17, v220, v17, s[48:49]
	v_fmamk_f32 v18, v203, 0x3fb8aa3b, v18
	v_cndmask_b32_e64 v32, v220, v18, s[50:51]
	v_fmac_f32_e32 v35, 0x3fb8aa3b, v202
	v_fmamk_f32 v25, v198, 0x3fb8aa3b, v33
	v_cndmask_b32_e64 v26, v220, v35, s[52:53]
	v_cndmask_b32_e64 v25, v220, v25, s[48:49]
	v_max_f32_e32 v33, v27, v26
	v_max3_f32 v33, v24, v25, v33
	v_fmac_f32_e32 v19, 0x3fb8aa3b, v206
	v_cndmask_b32_e64 v18, v220, v19, s[52:53]
	v_max_f32_e32 v34, v32, v18
	v_max3_f32 v34, v16, v17, v34
	v_fmamk_f32 v12, v207, 0x3fb8aa3b, v12
	v_cndmask_b32_e64 v12, v220, v12, s[38:39]
	v_fmamk_f32 v13, v208, 0x3fb8aa3b, v13
	v_cndmask_b32_e64 v13, v220, v13, s[40:41]
	v_fmamk_f32 v14, v209, 0x3fb8aa3b, v14
	v_cndmask_b32_e64 v19, v220, v14, s[42:43]
	v_fmamk_f32 v30, v204, 0x3fb8aa3b, v38
	v_fmac_f32_e32 v15, 0x3fb8aa3b, v210
	v_cndmask_b32_e64 v14, v220, v15, s[44:45]
	v_fmamk_f32 v8, v211, 0x3fb8aa3b, v8
	v_fmamk_f32 v21, v199, 0x3fb8aa3b, v29
	v_cndmask_b32_e64 v21, v220, v21, s[40:41]
	v_cndmask_b32_e64 v8, v220, v8, s[46:47]
	v_fmamk_f32 v9, v212, 0x3fb8aa3b, v9
	v_cndmask_b32_e64 v9, v220, v9, s[48:49]
	v_fmamk_f32 v10, v226, 0x3fb8aa3b, v10
	v_cndmask_b32_e64 v15, v220, v10, s[50:51]
	v_fmac_f32_e32 v31, 0x3fb8aa3b, v205
	v_cndmask_b32_e64 v22, v220, v31, s[44:45]
	v_cndmask_b32_e64 v31, v220, v30, s[42:43]
	v_fmac_f32_e32 v11, 0x3fb8aa3b, v227
	v_cndmask_b32_e64 v10, v220, v11, s[52:53]
	v_fmamk_f32 v4, v229, 0x3fb8aa3b, v4
	v_cndmask_b32_e64 v4, v220, v4, s[38:39]
	v_fmamk_f32 v5, v230, 0x3fb8aa3b, v5
	v_cndmask_b32_e64 v5, v220, v5, s[40:41]
	v_fmamk_f32 v6, v231, 0x3fb8aa3b, v6
	v_fmamk_f32 v20, v195, 0x3fb8aa3b, v28
	v_cndmask_b32_e64 v20, v220, v20, s[38:39]
	v_cndmask_b32_e64 v6, v220, v6, s[42:43]
	v_fmac_f32_e32 v7, 0x3fb8aa3b, v232
	v_cndmask_b32_e64 v7, v220, v7, s[44:45]
	v_fmamk_f32 v0, v234, 0x3fb8aa3b, v0
	v_fmamk_f32 v29, v213, 0x3fb8aa3b, v37
	v_cndmask_b32_e64 v29, v220, v29, s[40:41]
	v_cndmask_b32_e64 v0, v220, v0, s[46:47]
	v_fmamk_f32 v1, v235, 0x3fb8aa3b, v1
	v_fmamk_f32 v28, v233, 0x3fb8aa3b, v36
	v_cndmask_b32_e64 v28, v220, v28, s[38:39]
	v_cndmask_b32_e64 v1, v220, v1, s[48:49]
	v_fmamk_f32 v2, v236, 0x3fb8aa3b, v2
	v_fmac_f32_e32 v39, 0x3fb8aa3b, v228
	v_cndmask_b32_e64 v30, v220, v39, s[44:45]
	s_mov_b32 s20, 0xf149f2ca
	v_cndmask_b32_e64 v2, v220, v2, s[50:51]
	v_fmac_f32_e32 v3, 0x3fb8aa3b, v237
	v_max_f32_e32 v11, v23, v22
	v_max3_f32 v11, v20, v21, v11
	v_max3_f32 v11, v11, s20, v33
	v_max_f32_e32 v33, v31, v30
	v_max3_f32 v33, v28, v29, v33
	v_max3_f32 v11, v11, v33, v34
	v_max_f32_e32 v33, v19, v14
	v_max_f32_e32 v34, v15, v10
	v_cndmask_b32_e64 v3, v220, v3, s[52:53]
	v_max3_f32 v33, v12, v13, v33
	v_max3_f32 v34, v8, v9, v34
	v_max3_f32 v11, v11, v33, v34
	v_max_f32_e32 v33, v6, v7
	v_max_f32_e32 v34, v2, v3
	v_max3_f32 v33, v4, v5, v33
	v_max3_f32 v34, v0, v1, v34
	v_max3_f32 v11, v11, v33, v34
	v_and_b32_e32 v34, 64, v219
	v_xor_b32_e32 v33, 16, v219
	v_add_u32_e32 v34, 64, v34
	v_cmp_lt_i32_e32 vcc, v33, v34
	s_nop 1
	v_cndmask_b32_e32 v33, v219, v33, vcc
	v_lshlrev_b32_e32 v145, 2, v33
	ds_bpermute_b32 v33, v145, v11
	s_waitcnt lgkmcnt(0)
	v_max_f32_e32 v33, v33, v33
	v_max_f32_e32 v11, v11, v33
	v_xor_b32_e32 v33, 32, v219
	v_cmp_lt_i32_e32 vcc, v33, v34
	s_nop 1
	v_cndmask_b32_e32 v33, v219, v33, vcc
	v_lshlrev_b32_e32 v149, 2, v33
	ds_bpermute_b32 v33, v149, v11
	s_waitcnt lgkmcnt(0)
	v_max3_f32 v146, v11, v33, s20
	v_sub_f32_e32 v20, v20, v146
	v_exp_f32_e32 v33, v20
	v_sub_f32_e32 v21, v21, v146
	v_exp_f32_e32 v34, v21
	v_sub_f32_e32 v21, v23, v146
	v_exp_f32_e32 v35, v21
	v_sub_f32_e32 v21, v22, v146
	v_exp_f32_e32 v36, v21
	v_sub_f32_e32 v21, v24, v146
	v_add_f32_e32 v20, 0, v33
	v_exp_f32_e32 v24, v21
	v_sub_f32_e32 v21, v25, v146
	v_add_f32_e32 v20, v34, v20
	v_exp_f32_e32 v25, v21
	v_sub_f32_e32 v21, v27, v146
	v_add_f32_e32 v20, v35, v20
	v_exp_f32_e32 v27, v21
	v_sub_f32_e32 v21, v26, v146
	v_add_f32_e32 v20, v36, v20
	v_exp_f32_e32 v26, v21
	v_sub_f32_e32 v21, v28, v146
	v_add_f32_e32 v20, v24, v20
	v_exp_f32_e32 v28, v21
	v_sub_f32_e32 v21, v29, v146
	v_add_f32_e32 v20, v25, v20
	v_exp_f32_e32 v29, v21
	v_sub_f32_e32 v21, v31, v146
	v_add_f32_e32 v20, v27, v20
	v_exp_f32_e32 v31, v21
	v_sub_f32_e32 v21, v30, v146
	v_add_f32_e32 v20, v26, v20
	v_exp_f32_e32 v30, v21
	v_sub_f32_e32 v16, v16, v146
	v_add_f32_e32 v20, v28, v20
	v_exp_f32_e32 v37, v16
	v_sub_f32_e32 v17, v17, v146
	v_add_f32_e32 v20, v29, v20
	v_exp_f32_e32 v38, v17
	v_sub_f32_e32 v17, v32, v146
	v_add_f32_e32 v20, v31, v20
	v_exp_f32_e32 v32, v17
	v_sub_f32_e32 v17, v18, v146
	v_add_f32_e32 v20, v30, v20
	v_exp_f32_e32 v39, v17
	v_sub_f32_e32 v12, v12, v146
	v_add_f32_e32 v16, v37, v20
	v_exp_f32_e32 v40, v12
	v_sub_f32_e32 v13, v13, v146
	v_add_f32_e32 v16, v38, v16
	v_exp_f32_e32 v41, v13
	v_sub_f32_e32 v13, v19, v146
	v_add_f32_e32 v16, v32, v16
	v_exp_f32_e32 v42, v13
	v_sub_f32_e32 v13, v14, v146
	v_add_f32_e32 v16, v39, v16
	v_exp_f32_e32 v43, v13
	v_sub_f32_e32 v8, v8, v146
	v_add_f32_e32 v12, v40, v16
	v_exp_f32_e32 v44, v8
	v_sub_f32_e32 v9, v9, v146
	v_add_f32_e32 v12, v41, v12
	v_exp_f32_e32 v45, v9
	v_sub_f32_e32 v9, v15, v146
	v_add_f32_e32 v12, v42, v12
	v_exp_f32_e32 v46, v9
	v_sub_f32_e32 v9, v10, v146
	v_add_f32_e32 v12, v43, v12
	v_exp_f32_e32 v47, v9
	v_sub_f32_e32 v4, v4, v146
	v_add_f32_e32 v8, v44, v12
	v_exp_f32_e32 v48, v4
	v_sub_f32_e32 v5, v5, v146
	v_add_f32_e32 v8, v45, v8
	v_exp_f32_e32 v49, v5
	v_sub_f32_e32 v5, v6, v146
	v_add_f32_e32 v8, v46, v8
	v_exp_f32_e32 v50, v5
	v_sub_f32_e32 v5, v7, v146
	v_add_f32_e32 v8, v47, v8
	v_exp_f32_e32 v51, v5
	v_sub_f32_e32 v0, v0, v146
	v_add_f32_e32 v4, v48, v8
	v_exp_f32_e32 v52, v0
	v_sub_f32_e32 v1, v1, v146
	v_add_f32_e32 v4, v49, v4
	v_exp_f32_e32 v53, v1
	v_sub_f32_e32 v1, v2, v146
	v_add_f32_e32 v4, v50, v4
	v_exp_f32_e32 v54, v1
	v_sub_f32_e32 v1, v3, v146
	v_add_f32_e32 v4, v51, v4
	v_exp_f32_e32 v55, v1
	v_add_f32_e32 v0, v52, v4
	v_add_f32_e32 v0, v53, v0
	v_add_f32_e32 v0, v54, v0
	v_add_f32_e32 v0, v55, v0
	v_sub_f32_e32 v11, 0xf149f2ca, v146
	ds_bpermute_b32 v2, v145, v0
	v_exp_f32_e32 v1, v11
	s_or_b32 s20, s35, s60
	v_lshl_add_u32 v16, s20, 1, v121
	v_add_u32_e32 v12, v16, v123
	s_waitcnt lgkmcnt(0)
	v_add_f32_e32 v90, v0, v2
	v_mul_f32_e32 v20, 0, v1
	v_cvt_pk_bf16_f32 v0, v33, v34
	v_cvt_pk_bf16_f32 v1, v35, v36
	v_cvt_pk_bf16_f32 v2, v24, v25
	v_cvt_pk_bf16_f32 v3, v27, v26
	ds_read2_b64 v[4:7], v12 offset1:4
	v_add_u32_e32 v8, 0x4000, v12
	v_add_u32_e32 v12, 0x8000, v12
	v_add_u32_e32 v16, v16, v125
	ds_read2_b64 v[8:11], v8 offset0:32 offset1:36
	ds_read2_b64 v[12:15], v12 offset0:64 offset1:68
	ds_read2_b64 v[16:19], v16 offset1:4
	v_mov_b32_e32 v21, v20
	v_mov_b32_e32 v22, v20
	v_mov_b32_e32 v23, v20
	s_or_b32 s20, s34, s60
	ds_bpermute_b32 v91, v149, v90
	s_waitcnt lgkmcnt(4)
	v_mfma_f32_16x16x32_bf16 v[4:7], v[4:7], v[0:3], v[20:23]
	s_waitcnt lgkmcnt(3)
	v_mfma_f32_16x16x32_bf16 v[8:11], v[8:11], v[0:3], v[20:23]
	s_waitcnt lgkmcnt(2)
	v_mfma_f32_16x16x32_bf16 v[12:15], v[12:15], v[0:3], v[20:23]
	s_waitcnt lgkmcnt(1)
	v_mfma_f32_16x16x32_bf16 v[0:3], v[16:19], v[0:3], v[20:23]
	v_cvt_pk_bf16_f32 v16, v28, v29
	v_cvt_pk_bf16_f32 v17, v31, v30
	v_cvt_pk_bf16_f32 v18, v37, v38
	v_cvt_pk_bf16_f32 v19, v32, v39
	s_nop 2
	v_lshl_add_u32 v21, s20, 1, v121
	v_add_u32_e32 v26, v21, v123
	ds_read2_b64 v[22:25], v26 offset1:4
	s_waitcnt lgkmcnt(0)
	v_mfma_f32_16x16x32_bf16 v[4:7], v[22:25], v[16:19], v[4:7]
	v_add_u32_e32 v22, 0x4000, v26
	ds_read2_b64 v[22:25], v22 offset0:32 offset1:36
	v_add_u32_e32 v21, v21, v125
	s_waitcnt lgkmcnt(0)
	v_mfma_f32_16x16x32_bf16 v[8:11], v[22:25], v[16:19], v[8:11]
	v_add_u32_e32 v22, 0x8000, v26
	ds_read2_b64 v[22:25], v22 offset0:64 offset1:68
	s_or_b32 s20, s33, s60
	s_waitcnt lgkmcnt(0)
	v_mfma_f32_16x16x32_bf16 v[12:15], v[22:25], v[16:19], v[12:15]
	ds_read2_b64 v[22:25], v21 offset1:4
	v_lshl_add_u32 v21, s20, 1, v121
	v_add_u32_e32 v26, v21, v123
	s_waitcnt lgkmcnt(0)
	v_mfma_f32_16x16x32_bf16 v[0:3], v[22:25], v[16:19], v[0:3]
	v_cvt_pk_bf16_f32 v16, v40, v41
	v_cvt_pk_bf16_f32 v17, v42, v43
	v_cvt_pk_bf16_f32 v18, v44, v45
	v_cvt_pk_bf16_f32 v19, v46, v47
	ds_read2_b64 v[22:25], v26 offset1:4
	s_waitcnt lgkmcnt(0)
	v_mfma_f32_16x16x32_bf16 v[4:7], v[22:25], v[16:19], v[4:7]
	v_add_u32_e32 v22, 0x4000, v26
	ds_read2_b64 v[22:25], v22 offset0:32 offset1:36
	v_add_u32_e32 v21, v21, v125
	s_waitcnt lgkmcnt(0)
	v_mfma_f32_16x16x32_bf16 v[8:11], v[22:25], v[16:19], v[8:11]
	v_add_u32_e32 v22, 0x8000, v26
	ds_read2_b64 v[22:25], v22 offset0:64 offset1:68
	s_or_b32 s20, s26, s60
	s_waitcnt lgkmcnt(0)
	v_mfma_f32_16x16x32_bf16 v[12:15], v[22:25], v[16:19], v[12:15]
	ds_read2_b64 v[22:25], v21 offset1:4
	v_lshl_add_u32 v21, s20, 1, v121
	v_add_u32_e32 v26, v21, v123
	s_waitcnt lgkmcnt(0)
	v_mfma_f32_16x16x32_bf16 v[0:3], v[22:25], v[16:19], v[0:3]
	v_cvt_pk_bf16_f32 v16, v48, v49
	v_cvt_pk_bf16_f32 v17, v50, v51
	v_cvt_pk_bf16_f32 v18, v52, v53
	v_cvt_pk_bf16_f32 v19, v54, v55
	ds_read2_b64 v[22:25], v26 offset1:4
	s_waitcnt lgkmcnt(0)
	v_mfma_f32_16x16x32_bf16 v[4:7], v[22:25], v[16:19], v[4:7]
	v_add_u32_e32 v22, 0x4000, v26
	ds_read2_b64 v[22:25], v22 offset0:32 offset1:36
	v_add_u32_e32 v21, v21, v125
	s_waitcnt lgkmcnt(0)
	v_mfma_f32_16x16x32_bf16 v[8:11], v[22:25], v[16:19], v[8:11]
	v_add_u32_e32 v22, 0x8000, v26
	ds_read2_b64 v[22:25], v22 offset0:64 offset1:68
	s_or_b32 s20, s22, 1
	s_waitcnt lgkmcnt(0)
	v_mfma_f32_16x16x32_bf16 v[12:15], v[22:25], v[16:19], v[12:15]
	ds_read2_b64 v[22:25], v21 offset1:4
	s_waitcnt lgkmcnt(0)
	v_mfma_f32_16x16x32_bf16 v[16:19], v[22:25], v[16:19], v[0:3]
	s_nop 2
	v_sub_u32_e64 v0, s20, 4 clamp
	s_nop 0
	v_readfirstlane_b32 s21, v0
	s_min_u32 s21, s21, 8
	v_sub_u32_e64 v0, s20, 5 clamp
	v_cmp_ne_u32_e32 vcc, s21, v0
	s_cbranch_vccz .LBB0_120
	s_lshl_b32 s26, s21, 6
	s_add_i32 s33, s26, 0x1c0
	v_add_u32_e32 v0, s33, v108
	v_ashrrev_i32_e32 v1, 31, v0
	v_lshlrev_b64 v[0:1], 11, v[0:1]
	s_lshl_b32 s26, s21, 7
	v_lshl_add_u64 v[0:1], v[70:71], 0, v[0:1]
	v_lshl_add_u64 v[22:23], v[68:69], 0, s[26:27]
	s_barrier
	global_load_dwordx4 v[0:3], v[0:1], off
	s_nop 0
	global_load_dwordx4 v[22:25], v[22:23], off offset:896
	s_and_b32 s26, s33, 0x1c0
	v_add_u32_e32 v21, s26, v108
	v_mad_u64_u32 v[26:27], s[34:35], v21, s59, v[110:111]
	v_lshl_add_u32 v28, s26, 1, v109
	s_waitcnt vmcnt(1)
	ds_write_b128 v26, v[0:3]
	s_waitcnt vmcnt(0)
	ds_write_b128 v28, v[22:25]
	s_waitcnt lgkmcnt(0)
	s_barrier
.LBB0_120:
	v_lshl_or_b32 v0, s20, 6, v111
	v_or_b32_e32 v0, s2, v0
	v_mov_b32_e32 v1, s3
	v_lshlrev_b64 v[0:1], 11, v[0:1]
	v_lshl_add_u64 v[22:23], v[142:143], 0, v[0:1]
	global_load_dwordx4 v[0:3], v[22:23], off
	global_load_dwordx4 v[50:53], v[22:23], off offset:64
	s_add_i32 s21, s21, s61
	s_sub_i32 s20, s21, s20
	s_lshl_b32 s21, s21, 6
	s_and_b32 s35, s21, 0x1c0
	v_add_u32_e32 v21, s35, v115
	v_mad_u32_u24 v21, v21, s59, v117
	ds_read_b128 v[22:25], v21
	ds_read_b128 v[26:29], v21 offset:64
	v_add_u32_e32 v21, s35, v119
	v_mad_u32_u24 v21, v21, s59, v117
	s_add_i32 s26, s21, 64
	s_and_b32 s34, s26, 0x1c0
	s_and_b32 s33, s21, 0x140
	s_bitset1_b32 s33, 7
	s_addk_i32 s21, 0xc0
	s_and_b32 s26, s21, 0x1c0
	s_mul_i32 s20, s20, 31
	s_ashr_i32 s21, s20, 31
	s_lshl_b64 s[20:21], s[20:21], 2
	s_add_u32 s20, s36, s20
	s_addc_u32 s21, s23, s21
	global_load_dword v194, v99, s[20:21] offset:868
	global_load_dword v195, v96, s[20:21] offset:868
	global_load_dword v196, v98, s[20:21] offset:868
	global_load_dword v197, v94, s[20:21] offset:868
	global_load_dword v198, v97, s[20:21] offset:868
	global_load_dword v199, v93, s[20:21] offset:868
	global_load_dword v200, v95, s[20:21] offset:868
	global_load_dword v201, v92, s[20:21] offset:868
	global_load_dword v202, v99, s[20:21] offset:992
	global_load_dword v203, v96, s[20:21] offset:992
	global_load_dword v204, v98, s[20:21] offset:992
	global_load_dword v205, v94, s[20:21] offset:992
	global_load_dword v206, v97, s[20:21] offset:992
	global_load_dword v207, v93, s[20:21] offset:992
	global_load_dword v208, v95, s[20:21] offset:992
	global_load_dword v209, v92, s[20:21] offset:992
	global_load_dword v210, v99, s[20:21] offset:1116
	global_load_dword v211, v96, s[20:21] offset:1116
	global_load_dword v212, v98, s[20:21] offset:1116
	global_load_dword v213, v94, s[20:21] offset:1116
	global_load_dword v226, v97, s[20:21] offset:1116
	global_load_dword v227, v93, s[20:21] offset:1116
	global_load_dword v228, v95, s[20:21] offset:1116
	global_load_dword v229, v92, s[20:21] offset:1116
	global_load_dword v230, v99, s[20:21] offset:1240
	global_load_dword v231, v96, s[20:21] offset:1240
	global_load_dword v232, v98, s[20:21] offset:1240
	global_load_dword v233, v97, s[20:21] offset:1240
	global_load_dword v234, v93, s[20:21] offset:1240
	global_load_dword v235, v94, s[20:21] offset:1240
	global_load_dword v236, v95, s[20:21] offset:1240
	global_load_dword v237, v92, s[20:21] offset:1240
	s_waitcnt vmcnt(33) lgkmcnt(1)
	v_mfma_f32_16x16x32_bf16 v[22:25], v[22:25], v[0:3], 0
	s_waitcnt vmcnt(32) lgkmcnt(0)
	v_mfma_f32_16x16x32_bf16 v[46:49], v[26:29], v[50:53], v[22:25]
	s_nop 5
	ds_read_b128 v[22:25], v21
	ds_read_b128 v[26:29], v21 offset:64
	v_add_u32_e32 v21, s34, v115
	s_waitcnt lgkmcnt(1)
	v_mfma_f32_16x16x32_bf16 v[22:25], v[22:25], v[0:3], 0
	v_mad_u32_u24 v21, v21, s59, v117
	s_waitcnt lgkmcnt(0)
	v_mfma_f32_16x16x32_bf16 v[38:41], v[26:29], v[50:53], v[22:25]
	s_nop 4
	ds_read_b128 v[22:25], v21
	ds_read_b128 v[26:29], v21 offset:64
	v_add_u32_e32 v21, s34, v119
	v_mad_u32_u24 v21, v21, s59, v117
	s_waitcnt lgkmcnt(1)
	v_mfma_f32_16x16x32_bf16 v[22:25], v[22:25], v[0:3], 0
	s_waitcnt lgkmcnt(0)
	v_mfma_f32_16x16x32_bf16 v[42:45], v[26:29], v[50:53], v[22:25]
	s_nop 5
	ds_read_b128 v[22:25], v21
	ds_read_b128 v[26:29], v21 offset:64
	v_add_u32_e32 v21, s33, v115
	s_waitcnt lgkmcnt(1)
	v_mfma_f32_16x16x32_bf16 v[22:25], v[22:25], v[0:3], 0
	v_mad_u32_u24 v21, v21, s59, v117
	s_waitcnt lgkmcnt(0)
	v_mfma_f32_16x16x32_bf16 v[30:33], v[26:29], v[50:53], v[22:25]
	s_nop 4
	ds_read_b128 v[22:25], v21
	ds_read_b128 v[26:29], v21 offset:64
	v_add_u32_e32 v21, s33, v119
	v_mad_u32_u24 v21, v21, s59, v117
	s_waitcnt lgkmcnt(1)
	v_mfma_f32_16x16x32_bf16 v[22:25], v[22:25], v[0:3], 0
	s_waitcnt lgkmcnt(0)
	v_mfma_f32_16x16x32_bf16 v[34:37], v[26:29], v[50:53], v[22:25]
	s_nop 5
	ds_read_b128 v[22:25], v21
	ds_read_b128 v[26:29], v21 offset:64
	v_add_u32_e32 v21, s26, v115
	s_waitcnt lgkmcnt(1)
	v_mfma_f32_16x16x32_bf16 v[22:25], v[22:25], v[0:3], 0
	v_mad_u32_u24 v21, v21, s59, v117
	s_waitcnt lgkmcnt(0)
	v_mfma_f32_16x16x32_bf16 v[22:25], v[26:29], v[50:53], v[22:25]
	ds_read_b128 v[26:29], v21
	ds_read_b128 v[54:57], v21 offset:64
	v_add_u32_e32 v21, s26, v119
	v_mad_u32_u24 v21, v21, s59, v117
	s_waitcnt lgkmcnt(1)
	v_mfma_f32_16x16x32_bf16 v[26:29], v[26:29], v[0:3], 0
	s_waitcnt lgkmcnt(0)
	v_mfma_f32_16x16x32_bf16 v[26:29], v[54:57], v[50:53], v[26:29]
	ds_read_b128 v[54:57], v21
	ds_read_b128 v[58:61], v21 offset:64
	s_waitcnt lgkmcnt(1)
	v_mfma_f32_16x16x32_bf16 v[0:3], v[54:57], v[0:3], 0
	s_waitcnt vmcnt(0)
	v_fmamk_f32 v21, v194, 0x3fb8aa3b, v46
	s_waitcnt lgkmcnt(0)
	v_mfma_f32_16x16x32_bf16 v[0:3], v[58:61], v[50:53], v[0:3]
	v_cndmask_b32_e64 v21, v220, v21, s[38:39]
	v_fmamk_f32 v46, v195, 0x3fb8aa3b, v47
	v_cndmask_b32_e64 v46, v220, v46, s[40:41]
	v_fmamk_f32 v47, v196, 0x3fb8aa3b, v48
	v_cndmask_b32_e64 v48, v220, v47, s[42:43]
	v_fmac_f32_e32 v49, 0x3fb8aa3b, v197
	v_cndmask_b32_e64 v47, v220, v49, s[44:45]
	v_fmamk_f32 v38, v198, 0x3fb8aa3b, v38
	v_cndmask_b32_e64 v38, v220, v38, s[46:47]
	v_fmamk_f32 v39, v199, 0x3fb8aa3b, v39
	v_cndmask_b32_e64 v39, v220, v39, s[48:49]
	v_fmamk_f32 v40, v200, 0x3fb8aa3b, v40
	v_cndmask_b32_e64 v49, v220, v40, s[50:51]
	v_fmac_f32_e32 v41, 0x3fb8aa3b, v201
	v_cndmask_b32_e64 v40, v220, v41, s[52:53]
	v_fmamk_f32 v41, v202, 0x3fb8aa3b, v42
	v_cndmask_b32_e64 v41, v220, v41, s[38:39]
	v_fmamk_f32 v42, v203, 0x3fb8aa3b, v43
	v_cndmask_b32_e64 v42, v220, v42, s[40:41]
	v_fmamk_f32 v43, v204, 0x3fb8aa3b, v44
	v_cndmask_b32_e64 v44, v220, v43, s[42:43]
	v_fmac_f32_e32 v45, 0x3fb8aa3b, v205
	v_cndmask_b32_e64 v43, v220, v45, s[44:45]
	v_fmamk_f32 v30, v206, 0x3fb8aa3b, v30
	v_cndmask_b32_e64 v30, v220, v30, s[46:47]
	v_fmamk_f32 v31, v207, 0x3fb8aa3b, v31
	v_cndmask_b32_e64 v31, v220, v31, s[48:49]
	v_fmamk_f32 v32, v208, 0x3fb8aa3b, v32
	v_cndmask_b32_e64 v45, v220, v32, s[50:51]
	v_fmac_f32_e32 v33, 0x3fb8aa3b, v209
	v_cndmask_b32_e64 v32, v220, v33, s[52:53]
	v_max_f32_e32 v51, v45, v32
	v_max3_f32 v51, v30, v31, v51
	v_fmamk_f32 v33, v210, 0x3fb8aa3b, v34
	v_cndmask_b32_e64 v33, v220, v33, s[38:39]
	v_fmamk_f32 v34, v211, 0x3fb8aa3b, v35
	v_cndmask_b32_e64 v34, v220, v34, s[40:41]
	v_fmamk_f32 v35, v212, 0x3fb8aa3b, v36
	v_cndmask_b32_e64 v36, v220, v35, s[42:43]
	v_fmac_f32_e32 v37, 0x3fb8aa3b, v213
	v_cndmask_b32_e64 v35, v220, v37, s[44:45]
	v_fmamk_f32 v22, v226, 0x3fb8aa3b, v22
	v_cndmask_b32_e64 v22, v220, v22, s[46:47]
	v_fmamk_f32 v23, v227, 0x3fb8aa3b, v23
	v_cndmask_b32_e64 v37, v220, v23, s[48:49]
	v_fmamk_f32 v23, v228, 0x3fb8aa3b, v24
	v_cndmask_b32_e64 v50, v220, v23, s[50:51]
	v_fmac_f32_e32 v25, 0x3fb8aa3b, v229
	v_cndmask_b32_e64 v24, v220, v25, s[52:53]
	v_fmamk_f32 v23, v230, 0x3fb8aa3b, v26
	v_cndmask_b32_e64 v23, v220, v23, s[38:39]
	v_fmamk_f32 v26, v232, 0x3fb8aa3b, v28
	v_cndmask_b32_e64 v26, v220, v26, s[42:43]
	v_fmamk_f32 v0, v233, 0x3fb8aa3b, v0
	v_fmamk_f32 v25, v231, 0x3fb8aa3b, v27
	v_cndmask_b32_e64 v25, v220, v25, s[40:41]
	v_cndmask_b32_e64 v0, v220, v0, s[46:47]
	v_fmamk_f32 v1, v234, 0x3fb8aa3b, v1
	v_cndmask_b32_e64 v1, v220, v1, s[48:49]
	v_fmamk_f32 v2, v236, 0x3fb8aa3b, v2
	v_fmac_f32_e32 v29, 0x3fb8aa3b, v235
	v_cndmask_b32_e64 v27, v220, v29, s[44:45]
	v_max_f32_e32 v29, v49, v40
	v_max3_f32 v29, v38, v39, v29
	s_mov_b32 s20, 0xf149f2ca
	v_cndmask_b32_e64 v2, v220, v2, s[50:51]
	v_fmac_f32_e32 v3, 0x3fb8aa3b, v237
	v_max_f32_e32 v28, v48, v47
	v_max3_f32 v28, v21, v46, v28
	v_max3_f32 v28, v28, s20, v29
	v_max_f32_e32 v29, v44, v43
	v_max3_f32 v29, v41, v42, v29
	v_max3_f32 v28, v28, v29, v51
	v_max_f32_e32 v29, v36, v35
	v_max_f32_e32 v51, v50, v24
	v_cndmask_b32_e64 v3, v220, v3, s[52:53]
	v_max3_f32 v29, v33, v34, v29
	v_max3_f32 v51, v22, v37, v51
	v_max3_f32 v28, v28, v29, v51
	v_max_f32_e32 v29, v26, v27
	v_max_f32_e32 v51, v2, v3
	v_max3_f32 v29, v23, v25, v29
	v_max3_f32 v51, v0, v1, v51
	v_max3_f32 v28, v28, v29, v51
	ds_bpermute_b32 v29, v145, v28
	s_waitcnt lgkmcnt(0)
	v_max_f32_e32 v29, v29, v29
	v_max_f32_e32 v28, v28, v29
	ds_bpermute_b32 v29, v149, v28
	s_waitcnt lgkmcnt(0)
	v_max3_f32 v150, v28, v29, s20
	v_sub_f32_e32 v21, v21, v150
	v_exp_f32_e32 v29, v21
	v_sub_f32_e32 v46, v46, v150
	v_exp_f32_e32 v46, v46
	v_sub_f32_e32 v48, v48, v150
	v_exp_f32_e32 v48, v48
	v_sub_f32_e32 v47, v47, v150
	v_exp_f32_e32 v47, v47
	v_sub_f32_e32 v38, v38, v150
	v_add_f32_e32 v21, 0, v29
	v_exp_f32_e32 v38, v38
	v_sub_f32_e32 v39, v39, v150
	v_add_f32_e32 v21, v46, v21
	v_exp_f32_e32 v39, v39
	v_sub_f32_e32 v49, v49, v150
	v_add_f32_e32 v21, v48, v21
	v_exp_f32_e32 v49, v49
	v_sub_f32_e32 v40, v40, v150
	v_add_f32_e32 v21, v47, v21
	v_exp_f32_e32 v40, v40
	v_sub_f32_e32 v41, v41, v150
	v_add_f32_e32 v21, v38, v21
	v_exp_f32_e32 v41, v41
	v_sub_f32_e32 v42, v42, v150
	v_add_f32_e32 v21, v39, v21
	v_exp_f32_e32 v42, v42
	v_sub_f32_e32 v44, v44, v150
	v_add_f32_e32 v21, v49, v21
	v_exp_f32_e32 v44, v44
	v_sub_f32_e32 v43, v43, v150
	v_add_f32_e32 v21, v40, v21
	v_exp_f32_e32 v43, v43
	v_sub_f32_e32 v30, v30, v150
	v_add_f32_e32 v21, v41, v21
	v_exp_f32_e32 v51, v30
	v_sub_f32_e32 v30, v31, v150
	v_add_f32_e32 v21, v42, v21
	v_exp_f32_e32 v52, v30
	v_sub_f32_e32 v30, v45, v150
	v_add_f32_e32 v21, v44, v21
	v_exp_f32_e32 v45, v30
	v_sub_f32_e32 v30, v32, v150
	v_add_f32_e32 v21, v43, v21
	v_exp_f32_e32 v53, v30
	v_sub_f32_e32 v30, v33, v150
	v_add_f32_e32 v21, v51, v21
	v_exp_f32_e32 v54, v30
	v_sub_f32_e32 v30, v34, v150
	v_add_f32_e32 v21, v52, v21
	v_exp_f32_e32 v55, v30
	v_sub_f32_e32 v30, v36, v150
	v_add_f32_e32 v21, v45, v21
	v_exp_f32_e32 v56, v30
	v_sub_f32_e32 v30, v35, v150
	v_add_f32_e32 v21, v53, v21
	v_exp_f32_e32 v57, v30
	v_sub_f32_e32 v22, v22, v150
	v_add_f32_e32 v21, v54, v21
	v_exp_f32_e32 v62, v22
	v_sub_f32_e32 v22, v37, v150
	v_add_f32_e32 v21, v55, v21
	v_exp_f32_e32 v63, v22
	v_sub_f32_e32 v22, v50, v150
	v_add_f32_e32 v21, v56, v21
	v_exp_f32_e32 v50, v22
	v_sub_f32_e32 v22, v24, v150
	v_add_f32_e32 v21, v57, v21
	v_exp_f32_e32 v64, v22
	v_sub_f32_e32 v22, v23, v150
	v_add_f32_e32 v21, v62, v21
	v_exp_f32_e32 v65, v22
	v_sub_f32_e32 v22, v25, v150
	v_add_f32_e32 v21, v63, v21
	v_exp_f32_e32 v66, v22
	v_sub_f32_e32 v22, v26, v150
	v_add_f32_e32 v21, v50, v21
	v_exp_f32_e32 v67, v22
	v_sub_f32_e32 v22, v27, v150
	v_add_f32_e32 v21, v64, v21
	v_exp_f32_e32 v72, v22
	v_sub_f32_e32 v0, v0, v150
	v_add_f32_e32 v21, v65, v21
	v_exp_f32_e32 v73, v0
	v_sub_f32_e32 v1, v1, v150
	v_add_f32_e32 v21, v66, v21
	v_exp_f32_e32 v74, v1
	v_sub_f32_e32 v1, v2, v150
	v_add_f32_e32 v21, v67, v21
	v_exp_f32_e32 v75, v1
	v_sub_f32_e32 v1, v3, v150
	v_add_f32_e32 v21, v72, v21
	v_exp_f32_e32 v76, v1
	v_add_f32_e32 v0, v73, v21
	v_add_f32_e32 v0, v74, v0
	v_add_f32_e32 v0, v75, v0
	v_add_f32_e32 v0, v76, v0
	v_sub_f32_e32 v28, 0xf149f2ca, v150
	ds_bpermute_b32 v2, v145, v0
	v_exp_f32_e32 v1, v28
	s_or_b32 s20, s35, s60
	v_lshl_add_u32 v34, s20, 1, v121
	v_add_u32_e32 v30, v34, v123
	s_waitcnt lgkmcnt(0)
	v_add_f32_e32 v21, v0, v2
	v_mul_f32_e32 v58, 0, v1
	v_cvt_pk_bf16_f32 v0, v29, v46
	v_cvt_pk_bf16_f32 v1, v48, v47
	v_cvt_pk_bf16_f32 v2, v38, v39
	v_cvt_pk_bf16_f32 v3, v49, v40
	ds_read2_b64 v[22:25], v30 offset1:4
	v_add_u32_e32 v26, 0x4000, v30
	v_add_u32_e32 v30, 0x8000, v30
	v_add_u32_e32 v34, v34, v125
	ds_read2_b64 v[26:29], v26 offset0:32 offset1:36
	ds_read2_b64 v[30:33], v30 offset0:64 offset1:68
	ds_read2_b64 v[34:37], v34 offset1:4
	v_mov_b32_e32 v59, v58
	v_mov_b32_e32 v60, v58
	v_mov_b32_e32 v61, v58
	s_or_b32 s20, s34, s60
	ds_bpermute_b32 v100, v149, v21
	s_waitcnt lgkmcnt(4)
	v_mfma_f32_16x16x32_bf16 v[22:25], v[22:25], v[0:3], v[58:61]
	s_waitcnt lgkmcnt(3)
	v_mfma_f32_16x16x32_bf16 v[26:29], v[26:29], v[0:3], v[58:61]
	s_waitcnt lgkmcnt(2)
	v_mfma_f32_16x16x32_bf16 v[30:33], v[30:33], v[0:3], v[58:61]
	s_waitcnt lgkmcnt(1)
	v_mfma_f32_16x16x32_bf16 v[0:3], v[34:37], v[0:3], v[58:61]
	v_cvt_pk_bf16_f32 v34, v41, v42
	v_lshl_add_u32 v42, s20, 1, v121
	v_cvt_pk_bf16_f32 v35, v44, v43
	v_add_u32_e32 v43, v42, v123
	v_cvt_pk_bf16_f32 v36, v51, v52
	v_cvt_pk_bf16_f32 v37, v45, v53
	ds_read2_b64 v[38:41], v43 offset1:4
	s_waitcnt lgkmcnt(0)
	v_mfma_f32_16x16x32_bf16 v[22:25], v[38:41], v[34:37], v[22:25]
	v_add_u32_e32 v38, 0x4000, v43
	ds_read2_b64 v[38:41], v38 offset0:32 offset1:36
	s_or_b32 s20, s33, s60
	s_waitcnt lgkmcnt(0)
	v_mfma_f32_16x16x32_bf16 v[26:29], v[38:41], v[34:37], v[26:29]
	v_add_u32_e32 v38, 0x8000, v43
	ds_read2_b64 v[38:41], v38 offset0:64 offset1:68
	v_lshl_add_u32 v46, s20, 1, v121
	s_waitcnt lgkmcnt(0)
	v_mfma_f32_16x16x32_bf16 v[30:33], v[38:41], v[34:37], v[30:33]
	v_add_u32_e32 v38, v42, v125
	ds_read2_b64 v[38:41], v38 offset1:4
	v_add_u32_e32 v42, v46, v123
	s_waitcnt lgkmcnt(0)
	v_mfma_f32_16x16x32_bf16 v[0:3], v[38:41], v[34:37], v[0:3]
	v_cvt_pk_bf16_f32 v34, v54, v55
	v_cvt_pk_bf16_f32 v35, v56, v57
	v_cvt_pk_bf16_f32 v36, v62, v63
	v_cvt_pk_bf16_f32 v37, v50, v64
	ds_read2_b64 v[38:41], v42 offset1:4
	s_waitcnt lgkmcnt(0)
	v_mfma_f32_16x16x32_bf16 v[22:25], v[38:41], v[34:37], v[22:25]
	v_add_u32_e32 v38, 0x4000, v42
	ds_read2_b64 v[38:41], v38 offset0:32 offset1:36
	s_or_b32 s20, s26, s60
	s_waitcnt lgkmcnt(0)
	v_mfma_f32_16x16x32_bf16 v[38:41], v[38:41], v[34:37], v[26:29]
	s_nop 2
	v_add_u32_e32 v26, 0x8000, v42
	ds_read2_b64 v[26:29], v26 offset0:64 offset1:68
	v_lshl_add_u32 v50, s20, 1, v121
	s_waitcnt lgkmcnt(0)
	v_mfma_f32_16x16x32_bf16 v[42:45], v[26:29], v[34:37], v[30:33]
	v_add_u32_e32 v26, v46, v125
	ds_read2_b64 v[26:29], v26 offset1:4
	v_cvt_pk_bf16_f32 v46, v65, v66
	v_cvt_pk_bf16_f32 v47, v67, v72
	v_cvt_pk_bf16_f32 v48, v73, v74
	s_waitcnt lgkmcnt(0)
	v_mfma_f32_16x16x32_bf16 v[0:3], v[26:29], v[34:37], v[0:3]
	v_add_u32_e32 v34, v50, v123
	v_cvt_pk_bf16_f32 v49, v75, v76
	ds_read2_b64 v[26:29], v34 offset1:4
	s_waitcnt lgkmcnt(0)
	v_mfma_f32_16x16x32_bf16 v[26:29], v[26:29], v[46:49], v[22:25]
	s_nop 2
	v_add_u32_e32 v22, 0x4000, v34
	ds_read2_b64 v[22:25], v22 offset0:32 offset1:36
	s_or_b32 s20, s22, 2
	s_waitcnt lgkmcnt(0)
	v_mfma_f32_16x16x32_bf16 v[30:33], v[22:25], v[46:49], v[38:41]
	v_add_u32_e32 v22, 0x8000, v34
	ds_read2_b64 v[22:25], v22 offset0:64 offset1:68
	s_waitcnt lgkmcnt(0)
	v_mfma_f32_16x16x32_bf16 v[34:37], v[22:25], v[46:49], v[42:45]
	v_add_u32_e32 v22, v50, v125
	ds_read2_b64 v[22:25], v22 offset1:4
	s_waitcnt lgkmcnt(0)
	v_mfma_f32_16x16x32_bf16 v[38:41], v[22:25], v[46:49], v[0:3]
	s_nop 2
	v_sub_u32_e64 v0, s20, 4 clamp
	s_nop 0
	v_readfirstlane_b32 s21, v0
	v_sub_u32_e64 v0, s20, 5 clamp
	s_min_u32 s21, s21, 8
	v_min_u32_e32 v0, 8, v0
	v_cmp_eq_u32_e32 vcc, s21, v0
	s_cbranch_vccnz .LBB0_122
	s_lshl_b32 s26, s21, 6
	s_add_i32 s33, s26, 0x1c0
	v_add_u32_e32 v0, s33, v108
	v_ashrrev_i32_e32 v1, 31, v0
	v_lshlrev_b64 v[0:1], 11, v[0:1]
	s_lshl_b32 s26, s21, 7
	v_lshl_add_u64 v[0:1], v[70:71], 0, v[0:1]
	v_lshl_add_u64 v[22:23], v[68:69], 0, s[26:27]
	s_barrier
	global_load_dwordx4 v[0:3], v[0:1], off
	s_nop 0
	global_load_dwordx4 v[22:25], v[22:23], off offset:896
	s_and_b32 s26, s33, 0x1c0
	v_add_u32_e32 v42, s26, v108
	v_mad_u64_u32 v[42:43], s[34:35], v42, s59, v[110:111]
	v_lshl_add_u32 v44, s26, 1, v109
	s_waitcnt vmcnt(1)
	ds_write_b128 v42, v[0:3]
	s_waitcnt vmcnt(0)
	ds_write_b128 v44, v[22:25]
	s_waitcnt lgkmcnt(0)
	s_barrier
.LBB0_122:
	v_lshl_or_b32 v0, s20, 6, v111
	v_or_b32_e32 v0, s2, v0
	v_mov_b32_e32 v1, s3
	v_lshlrev_b64 v[0:1], 11, v[0:1]
	v_lshl_add_u64 v[22:23], v[142:143], 0, v[0:1]
	global_load_dwordx4 v[0:3], v[22:23], off
	global_load_dwordx4 v[72:75], v[22:23], off offset:64
	s_add_i32 s21, s21, s61
	s_sub_i32 s20, s21, s20
	s_lshl_b32 s21, s21, 6
	s_and_b32 s35, s21, 0x1c0
	v_add_u32_e32 v22, s35, v115
	v_mad_u32_u24 v42, v22, s59, v117
	ds_read_b128 v[22:25], v42
	ds_read_b128 v[42:45], v42 offset:64
	s_and_b32 s26, s21, 0x180
	s_or_b32 s34, s26, 64
	s_add_i32 s26, s21, 0x80
	s_and_b32 s33, s26, 0x1c0
	s_addk_i32 s21, 0xc0
	s_and_b32 s26, s21, 0x1c0
	s_mul_i32 s20, s20, 31
	s_ashr_i32 s21, s20, 31
	s_lshl_b64 s[20:21], s[20:21], 2
	s_add_u32 s20, s36, s20
	s_addc_u32 s21, s23, s21
	global_load_dword v194, v99, s[20:21] offset:868
	global_load_dword v195, v96, s[20:21] offset:868
	global_load_dword v196, v98, s[20:21] offset:868
	global_load_dword v197, v94, s[20:21] offset:868
	global_load_dword v198, v97, s[20:21] offset:868
	global_load_dword v199, v93, s[20:21] offset:868
	global_load_dword v200, v95, s[20:21] offset:868
	global_load_dword v201, v92, s[20:21] offset:868
	global_load_dword v202, v99, s[20:21] offset:992
	global_load_dword v203, v96, s[20:21] offset:992
	global_load_dword v204, v98, s[20:21] offset:992
	global_load_dword v205, v94, s[20:21] offset:992
	global_load_dword v206, v97, s[20:21] offset:992
	global_load_dword v207, v93, s[20:21] offset:992
	global_load_dword v208, v95, s[20:21] offset:992
	global_load_dword v209, v92, s[20:21] offset:992
	global_load_dword v210, v99, s[20:21] offset:1116
	global_load_dword v211, v96, s[20:21] offset:1116
	global_load_dword v212, v98, s[20:21] offset:1116
	global_load_dword v213, v94, s[20:21] offset:1116
	global_load_dword v226, v97, s[20:21] offset:1116
	global_load_dword v227, v93, s[20:21] offset:1116
	global_load_dword v228, v95, s[20:21] offset:1116
	global_load_dword v229, v92, s[20:21] offset:1116
	global_load_dword v230, v99, s[20:21] offset:1240
	global_load_dword v231, v96, s[20:21] offset:1240
	global_load_dword v232, v98, s[20:21] offset:1240
	global_load_dword v233, v97, s[20:21] offset:1240
	global_load_dword v234, v93, s[20:21] offset:1240
	global_load_dword v235, v94, s[20:21] offset:1240
	global_load_dword v236, v95, s[20:21] offset:1240
	global_load_dword v237, v92, s[20:21] offset:1240
	v_readlane_b32 s92, v252, 60
	s_mov_b64 s[90:91], s[0:1]
	v_readlane_b32 s93, v252, 61
	s_waitcnt vmcnt(33) lgkmcnt(1)
	v_mfma_f32_16x16x32_bf16 v[22:25], v[22:25], v[0:3], 0
	s_waitcnt vmcnt(32) lgkmcnt(0)
	v_mfma_f32_16x16x32_bf16 v[64:67], v[42:45], v[72:75], v[22:25]
	s_nop 5
	v_add_u32_e32 v22, s35, v119
	v_mad_u32_u24 v42, v22, s59, v117
	ds_read_b128 v[22:25], v42
	ds_read_b128 v[42:45], v42 offset:64
	s_waitcnt lgkmcnt(1)
	v_mfma_f32_16x16x32_bf16 v[22:25], v[22:25], v[0:3], 0
	s_waitcnt lgkmcnt(0)
	v_mfma_f32_16x16x32_bf16 v[54:57], v[42:45], v[72:75], v[22:25]
	s_nop 5
	v_add_u32_e32 v22, s34, v115
	v_mad_u32_u24 v42, v22, s59, v117
	ds_read_b128 v[22:25], v42
	ds_read_b128 v[42:45], v42 offset:64
	s_waitcnt lgkmcnt(1)
	v_mfma_f32_16x16x32_bf16 v[22:25], v[22:25], v[0:3], 0
	s_waitcnt lgkmcnt(0)
	v_mfma_f32_16x16x32_bf16 v[60:63], v[42:45], v[72:75], v[22:25]
	s_nop 5
	v_add_u32_e32 v22, s34, v119
	v_mad_u32_u24 v42, v22, s59, v117
	ds_read_b128 v[22:25], v42
	ds_read_b128 v[42:45], v42 offset:64
	s_waitcnt lgkmcnt(1)
	v_mfma_f32_16x16x32_bf16 v[22:25], v[22:25], v[0:3], 0
	s_waitcnt lgkmcnt(0)
	v_mfma_f32_16x16x32_bf16 v[46:49], v[42:45], v[72:75], v[22:25]
	s_nop 5
	v_add_u32_e32 v22, s33, v115
	v_mad_u32_u24 v42, v22, s59, v117
	ds_read_b128 v[22:25], v42
	ds_read_b128 v[42:45], v42 offset:64
	s_waitcnt lgkmcnt(1)
	v_mfma_f32_16x16x32_bf16 v[22:25], v[22:25], v[0:3], 0
	s_waitcnt lgkmcnt(0)
	v_mfma_f32_16x16x32_bf16 v[50:53], v[42:45], v[72:75], v[22:25]
	s_nop 5
	v_add_u32_e32 v22, s33, v119
	v_mad_u32_u24 v42, v22, s59, v117
	ds_read_b128 v[22:25], v42
	ds_read_b128 v[42:45], v42 offset:64
	s_waitcnt lgkmcnt(1)
	v_mfma_f32_16x16x32_bf16 v[22:25], v[22:25], v[0:3], 0
	s_waitcnt lgkmcnt(0)
	v_mfma_f32_16x16x32_bf16 v[22:25], v[42:45], v[72:75], v[22:25]
	v_add_u32_e32 v42, s26, v115
	v_mad_u32_u24 v59, v42, s59, v117
	ds_read_b128 v[42:45], v59
	ds_read_b128 v[76:79], v59 offset:64
	s_waitcnt lgkmcnt(1)
	v_mfma_f32_16x16x32_bf16 v[42:45], v[42:45], v[0:3], 0
	v_add_u32_e32 v59, s26, v119
	v_mad_u32_u24 v59, v59, s59, v117
	s_waitcnt lgkmcnt(0)
	v_mfma_f32_16x16x32_bf16 v[42:45], v[76:79], v[72:75], v[42:45]
	ds_read_b128 v[76:79], v59
	ds_read_b128 v[80:83], v59 offset:64
	s_waitcnt lgkmcnt(1)
	v_mfma_f32_16x16x32_bf16 v[0:3], v[76:79], v[0:3], 0
	s_waitcnt vmcnt(0)
	v_fmamk_f32 v59, v194, 0x3fb8aa3b, v64
	s_waitcnt lgkmcnt(0)
	v_mfma_f32_16x16x32_bf16 v[0:3], v[80:83], v[72:75], v[0:3]
	v_cndmask_b32_e64 v59, v220, v59, s[38:39]
	v_fmamk_f32 v64, v195, 0x3fb8aa3b, v65
	v_cndmask_b32_e64 v64, v220, v64, s[40:41]
	v_fmamk_f32 v65, v196, 0x3fb8aa3b, v66
	v_cndmask_b32_e64 v66, v220, v65, s[42:43]
	v_fmac_f32_e32 v67, 0x3fb8aa3b, v197
	v_cndmask_b32_e64 v65, v220, v67, s[44:45]
	v_fmamk_f32 v54, v198, 0x3fb8aa3b, v54
	v_cndmask_b32_e64 v54, v220, v54, s[46:47]
	v_fmamk_f32 v55, v199, 0x3fb8aa3b, v55
	v_cndmask_b32_e64 v55, v220, v55, s[48:49]
	v_fmamk_f32 v56, v200, 0x3fb8aa3b, v56
	v_cndmask_b32_e64 v67, v220, v56, s[50:51]
	v_fmac_f32_e32 v57, 0x3fb8aa3b, v201
	v_cndmask_b32_e64 v56, v220, v57, s[52:53]
	v_fmamk_f32 v57, v202, 0x3fb8aa3b, v60
	v_cndmask_b32_e64 v57, v220, v57, s[38:39]
	v_fmamk_f32 v60, v203, 0x3fb8aa3b, v61
	v_cndmask_b32_e64 v60, v220, v60, s[40:41]
	v_fmamk_f32 v61, v204, 0x3fb8aa3b, v62
	v_cndmask_b32_e64 v62, v220, v61, s[42:43]
	v_fmac_f32_e32 v63, 0x3fb8aa3b, v205
	v_cndmask_b32_e64 v61, v220, v63, s[44:45]
	v_fmamk_f32 v46, v206, 0x3fb8aa3b, v46
	v_cndmask_b32_e64 v46, v220, v46, s[46:47]
	v_fmamk_f32 v47, v207, 0x3fb8aa3b, v47
	v_cndmask_b32_e64 v47, v220, v47, s[48:49]
	v_fmamk_f32 v48, v208, 0x3fb8aa3b, v48
	v_cndmask_b32_e64 v63, v220, v48, s[50:51]
	v_fmac_f32_e32 v49, 0x3fb8aa3b, v209
	v_cndmask_b32_e64 v48, v220, v49, s[52:53]
	v_max_f32_e32 v73, v63, v48
	v_max3_f32 v73, v46, v47, v73
	v_fmamk_f32 v49, v210, 0x3fb8aa3b, v50
	v_cndmask_b32_e64 v49, v220, v49, s[38:39]
	v_fmamk_f32 v50, v211, 0x3fb8aa3b, v51
	v_cndmask_b32_e64 v50, v220, v50, s[40:41]
	v_fmamk_f32 v51, v212, 0x3fb8aa3b, v52
	v_cndmask_b32_e64 v52, v220, v51, s[42:43]
	v_fmac_f32_e32 v53, 0x3fb8aa3b, v213
	v_cndmask_b32_e64 v51, v220, v53, s[44:45]
	v_fmamk_f32 v22, v226, 0x3fb8aa3b, v22
	v_cndmask_b32_e64 v22, v220, v22, s[46:47]
	v_fmamk_f32 v23, v227, 0x3fb8aa3b, v23
	v_cndmask_b32_e64 v53, v220, v23, s[48:49]
	v_fmamk_f32 v23, v228, 0x3fb8aa3b, v24
	v_cndmask_b32_e64 v72, v220, v23, s[50:51]
	v_fmac_f32_e32 v25, 0x3fb8aa3b, v229
	v_cndmask_b32_e64 v24, v220, v25, s[52:53]
	v_fmamk_f32 v23, v230, 0x3fb8aa3b, v42
	v_cndmask_b32_e64 v23, v220, v23, s[38:39]
	v_fmamk_f32 v42, v232, 0x3fb8aa3b, v44
	v_cndmask_b32_e64 v42, v220, v42, s[42:43]
	v_fmamk_f32 v0, v233, 0x3fb8aa3b, v0
	v_fmamk_f32 v25, v231, 0x3fb8aa3b, v43
	v_cndmask_b32_e64 v25, v220, v25, s[40:41]
	v_cndmask_b32_e64 v0, v220, v0, s[46:47]
	v_fmamk_f32 v1, v234, 0x3fb8aa3b, v1
	v_cndmask_b32_e64 v1, v220, v1, s[48:49]
	v_fmamk_f32 v2, v236, 0x3fb8aa3b, v2
	v_fmac_f32_e32 v45, 0x3fb8aa3b, v235
	v_cndmask_b32_e64 v43, v220, v45, s[44:45]
	v_max_f32_e32 v45, v67, v56
	v_max3_f32 v45, v54, v55, v45
	s_mov_b32 s20, 0xf149f2ca
	v_cndmask_b32_e64 v2, v220, v2, s[50:51]
	v_fmac_f32_e32 v3, 0x3fb8aa3b, v237
	v_max_f32_e32 v44, v66, v65
	v_max3_f32 v44, v59, v64, v44
	v_max3_f32 v44, v44, s20, v45
	v_max_f32_e32 v45, v62, v61
	v_max3_f32 v45, v57, v60, v45
	v_max3_f32 v44, v44, v45, v73
	v_max_f32_e32 v45, v52, v51
	v_max_f32_e32 v73, v72, v24
	v_cndmask_b32_e64 v3, v220, v3, s[52:53]
	v_max3_f32 v45, v49, v50, v45
	v_max3_f32 v73, v22, v53, v73
	v_max3_f32 v44, v44, v45, v73
	v_max_f32_e32 v45, v42, v43
	v_max_f32_e32 v73, v2, v3
	v_max3_f32 v45, v23, v25, v45
	v_max3_f32 v73, v0, v1, v73
	v_max3_f32 v44, v44, v45, v73
	ds_bpermute_b32 v45, v145, v44
	s_waitcnt lgkmcnt(0)
	v_max_f32_e32 v45, v45, v45
	v_max_f32_e32 v44, v44, v45
	ds_bpermute_b32 v45, v149, v44
	s_waitcnt lgkmcnt(0)
	v_max3_f32 v153, v44, v45, s20
	v_sub_f32_e32 v45, v59, v153
	v_exp_f32_e32 v45, v45
	v_sub_f32_e32 v64, v64, v153
	v_exp_f32_e32 v64, v64
	v_sub_f32_e32 v66, v66, v153
	v_exp_f32_e32 v66, v66
	v_sub_f32_e32 v65, v65, v153
	v_exp_f32_e32 v65, v65
	v_sub_f32_e32 v54, v54, v153
	v_add_f32_e32 v59, 0, v45
	v_exp_f32_e32 v54, v54
	v_sub_f32_e32 v55, v55, v153
	v_add_f32_e32 v59, v64, v59
	v_exp_f32_e32 v55, v55
	v_sub_f32_e32 v67, v67, v153
	v_add_f32_e32 v59, v66, v59
	v_exp_f32_e32 v67, v67
	v_sub_f32_e32 v56, v56, v153
	v_add_f32_e32 v59, v65, v59
	v_exp_f32_e32 v56, v56
	v_sub_f32_e32 v57, v57, v153
	v_add_f32_e32 v59, v54, v59
	v_exp_f32_e32 v73, v57
	v_add_f32_e32 v59, v55, v59
	v_add_f32_e32 v59, v67, v59
	v_add_f32_e32 v59, v56, v59
	v_add_f32_e32 v57, v73, v59
	v_sub_f32_e32 v59, v60, v153
	v_exp_f32_e32 v59, v59
	v_sub_f32_e32 v60, v62, v153
	v_exp_f32_e32 v60, v60
	v_sub_f32_e32 v61, v61, v153
	v_exp_f32_e32 v61, v61
	v_sub_f32_e32 v46, v46, v153
	v_exp_f32_e32 v62, v46
	v_sub_f32_e32 v47, v47, v153
	v_add_f32_e32 v57, v59, v57
	v_exp_f32_e32 v74, v47
	v_sub_f32_e32 v47, v63, v153
	v_add_f32_e32 v57, v60, v57
	v_exp_f32_e32 v63, v47
	v_sub_f32_e32 v47, v48, v153
	v_add_f32_e32 v57, v61, v57
	v_exp_f32_e32 v75, v47
	v_sub_f32_e32 v47, v49, v153
	v_add_f32_e32 v46, v62, v57
	v_exp_f32_e32 v76, v47
	v_sub_f32_e32 v47, v50, v153
	v_add_f32_e32 v46, v74, v46
	v_exp_f32_e32 v77, v47
	v_sub_f32_e32 v47, v52, v153
	v_add_f32_e32 v46, v63, v46
	v_exp_f32_e32 v78, v47
	v_sub_f32_e32 v47, v51, v153
	v_add_f32_e32 v46, v75, v46
	v_exp_f32_e32 v79, v47
	v_sub_f32_e32 v22, v22, v153
	v_add_f32_e32 v46, v76, v46
	v_exp_f32_e32 v80, v22
	v_add_f32_e32 v46, v77, v46
	v_add_f32_e32 v46, v78, v46
	v_add_f32_e32 v46, v79, v46
	v_add_f32_e32 v22, v80, v46
	v_sub_f32_e32 v46, v53, v153
	v_exp_f32_e32 v81, v46
	v_sub_f32_e32 v46, v72, v153
	v_exp_f32_e32 v72, v46
	v_sub_f32_e32 v24, v24, v153
	v_exp_f32_e32 v82, v24
	v_sub_f32_e32 v23, v23, v153
	v_exp_f32_e32 v83, v23
	v_sub_f32_e32 v23, v25, v153
	v_add_f32_e32 v22, v81, v22
	v_exp_f32_e32 v84, v23
	v_sub_f32_e32 v23, v42, v153
	v_add_f32_e32 v22, v72, v22
	v_exp_f32_e32 v85, v23
	v_sub_f32_e32 v23, v43, v153
	v_add_f32_e32 v22, v82, v22
	v_exp_f32_e32 v86, v23
	v_sub_f32_e32 v0, v0, v153
	v_add_f32_e32 v22, v83, v22
	v_exp_f32_e32 v87, v0
	v_add_f32_e32 v22, v84, v22
	v_sub_f32_e32 v1, v1, v153
	v_add_f32_e32 v22, v85, v22
	v_exp_f32_e32 v101, v1
	v_sub_f32_e32 v1, v2, v153
	v_add_f32_e32 v22, v86, v22
	v_exp_f32_e32 v102, v1
	v_sub_f32_e32 v1, v3, v153
	s_or_b32 s20, s35, s60
	v_add_f32_e32 v0, v87, v22
	v_exp_f32_e32 v103, v1
	v_cvt_pk_bf16_f32 v22, v45, v64
	v_cvt_pk_bf16_f32 v23, v66, v65
	v_cvt_pk_bf16_f32 v24, v54, v55
	v_lshl_add_u32 v54, s20, 1, v121
	v_sub_f32_e32 v44, 0xf149f2ca, v153
	v_add_u32_e32 v50, v54, v123
	v_add_f32_e32 v0, v101, v0
	v_exp_f32_e32 v1, v44
	v_cvt_pk_bf16_f32 v25, v67, v56
	ds_read2_b64 v[42:45], v50 offset1:4
	v_add_u32_e32 v46, 0x4000, v50
	v_add_u32_e32 v50, 0x8000, v50
	v_add_u32_e32 v54, v54, v125
	v_add_f32_e32 v0, v102, v0
	ds_read2_b64 v[46:49], v46 offset0:32 offset1:36
	ds_read2_b64 v[50:53], v50 offset0:64 offset1:68
	ds_read2_b64 v[54:57], v54 offset1:4
	v_add_f32_e32 v0, v103, v0
	ds_bpermute_b32 v2, v145, v0
	s_or_b32 s20, s34, s60
	s_waitcnt lgkmcnt(0)
	v_add_f32_e32 v156, v0, v2
	v_mul_f32_e32 v0, 0, v1
	v_mov_b32_e32 v1, v0
	v_mov_b32_e32 v2, v0
	v_mov_b32_e32 v3, v0
	ds_bpermute_b32 v157, v149, v156
	s_nop 0
	v_mfma_f32_16x16x32_bf16 v[42:45], v[42:45], v[22:25], v[0:3]
	v_mfma_f32_16x16x32_bf16 v[46:49], v[46:49], v[22:25], v[0:3]
	v_mfma_f32_16x16x32_bf16 v[50:53], v[50:53], v[22:25], v[0:3]
	v_mfma_f32_16x16x32_bf16 v[22:25], v[54:57], v[22:25], v[0:3]
	v_cvt_pk_bf16_f32 v54, v73, v59
	v_cvt_pk_bf16_f32 v55, v60, v61
	v_cvt_pk_bf16_f32 v56, v62, v74
	v_cvt_pk_bf16_f32 v57, v63, v75
	s_nop 2
	v_lshl_add_u32 v1, s20, 1, v121
	v_add_u32_e32 v2, v1, v123
	ds_read2_b64 v[60:63], v2 offset1:4
	v_add_u32_e32 v3, 0x4000, v2
	s_waitcnt lgkmcnt(0)
	v_mfma_f32_16x16x32_bf16 v[42:45], v[60:63], v[54:57], v[42:45]
	ds_read2_b64 v[60:63], v3 offset0:32 offset1:36
	v_add_u32_e32 v2, 0x8000, v2
	v_add_u32_e32 v1, v1, v125
	s_waitcnt lgkmcnt(0)
	v_mfma_f32_16x16x32_bf16 v[46:49], v[60:63], v[54:57], v[46:49]
	ds_read2_b64 v[60:63], v2 offset0:64 offset1:68
	s_or_b32 s20, s33, s60
	s_waitcnt lgkmcnt(0)
	v_mfma_f32_16x16x32_bf16 v[50:53], v[60:63], v[54:57], v[50:53]
	ds_read2_b64 v[60:63], v1 offset1:4
	v_lshl_add_u32 v1, s20, 1, v121
	v_add_u32_e32 v2, v1, v123
	s_waitcnt lgkmcnt(0)
	v_mfma_f32_16x16x32_bf16 v[22:25], v[60:63], v[54:57], v[22:25]
	v_cvt_pk_bf16_f32 v54, v76, v77
	v_cvt_pk_bf16_f32 v55, v78, v79
	v_cvt_pk_bf16_f32 v56, v80, v81
	v_cvt_pk_bf16_f32 v57, v72, v82
	ds_read2_b64 v[60:63], v2 offset1:4
	v_add_u32_e32 v3, 0x4000, v2
	s_waitcnt lgkmcnt(0)
	v_mfma_f32_16x16x32_bf16 v[42:45], v[60:63], v[54:57], v[42:45]
	ds_read2_b64 v[60:63], v3 offset0:32 offset1:36
	v_add_u32_e32 v2, 0x8000, v2
	v_add_u32_e32 v1, v1, v125
	s_waitcnt lgkmcnt(0)
	v_mfma_f32_16x16x32_bf16 v[46:49], v[60:63], v[54:57], v[46:49]
	ds_read2_b64 v[60:63], v2 offset0:64 offset1:68
	s_or_b32 s20, s26, s60
	s_waitcnt lgkmcnt(0)
	v_mfma_f32_16x16x32_bf16 v[50:53], v[60:63], v[54:57], v[50:53]
	ds_read2_b64 v[60:63], v1 offset1:4
	v_lshl_add_u32 v1, s20, 1, v121
	v_add_u32_e32 v2, v1, v123
	s_waitcnt lgkmcnt(0)
	v_mfma_f32_16x16x32_bf16 v[22:25], v[60:63], v[54:57], v[22:25]
	v_cvt_pk_bf16_f32 v54, v83, v84
	v_cvt_pk_bf16_f32 v55, v85, v86
	v_cvt_pk_bf16_f32 v56, v87, v101
	v_cvt_pk_bf16_f32 v57, v102, v103
	ds_read2_b64 v[60:63], v2 offset1:4
	v_add_u32_e32 v3, 0x4000, v2
	s_waitcnt lgkmcnt(0)
	v_mfma_f32_16x16x32_bf16 v[42:45], v[60:63], v[54:57], v[42:45]
	ds_read2_b64 v[60:63], v3 offset0:32 offset1:36
	v_add_u32_e32 v2, 0x8000, v2
	v_add_u32_e32 v1, v1, v125
	s_waitcnt lgkmcnt(0)
	v_mfma_f32_16x16x32_bf16 v[46:49], v[60:63], v[54:57], v[46:49]
	ds_read2_b64 v[60:63], v2 offset0:64 offset1:68
	s_or_b32 s20, s22, 3
	s_waitcnt lgkmcnt(0)
	v_mfma_f32_16x16x32_bf16 v[50:53], v[60:63], v[54:57], v[50:53]
	ds_read2_b64 v[60:63], v1 offset1:4
	v_sub_u32_e64 v1, s20, 4 clamp
	s_waitcnt lgkmcnt(0)
	v_mfma_f32_16x16x32_bf16 v[54:57], v[60:63], v[54:57], v[22:25]
	v_readfirstlane_b32 s21, v1
	v_sub_u32_e64 v1, s20, 5 clamp
	s_min_u32 s21, s21, 8
	v_min_u32_e32 v1, 8, v1
	v_cmp_eq_u32_e32 vcc, s21, v1
	s_cbranch_vccnz .LBB0_124
	s_lshl_b32 s22, s21, 6
	s_addk_i32 s22, 0x1c0
	v_add_u32_e32 v2, s22, v108
	v_ashrrev_i32_e32 v3, 31, v2
	v_lshlrev_b64 v[2:3], 11, v[2:3]
	s_lshl_b32 s26, s21, 7
	v_lshl_add_u64 v[2:3], v[70:71], 0, v[2:3]
	v_lshl_add_u64 v[60:61], v[68:69], 0, s[26:27]
	s_barrier
	global_load_dwordx4 v[22:25], v[2:3], off
	s_nop 0
	global_load_dwordx4 v[60:63], v[60:61], off offset:896
	s_and_b32 s22, s22, 0x1c0
	v_add_u32_e32 v1, s22, v108
	v_mad_u64_u32 v[2:3], s[34:35], v1, s59, v[110:111]
	v_lshl_add_u32 v59, s22, 1, v109
	s_waitcnt vmcnt(1)
	ds_write_b128 v2, v[22:25]
	s_waitcnt vmcnt(0)
	ds_write_b128 v59, v[60:63]
	s_waitcnt lgkmcnt(0)
	s_barrier
.LBB0_124:
	v_lshl_or_b32 v1, s20, 6, v111
	v_or_b32_e32 v2, s2, v1
	v_mov_b32_e32 v3, s3
	v_lshlrev_b64 v[2:3], 11, v[2:3]
	v_lshl_add_u64 v[2:3], v[142:143], 0, v[2:3]
	global_load_dwordx4 v[22:25], v[2:3], off
	global_load_dwordx4 v[102:105], v[2:3], off offset:64
	s_add_i32 s21, s21, s61
	s_lshl_b32 s2, s21, 6
	s_and_b32 s33, s2, 0x1c0
	v_add_u32_e32 v1, s33, v115
	v_mad_u32_u24 v1, v1, s59, v117
	ds_read_b128 v[60:63], v1
	ds_read_b128 v[64:67], v1 offset:64
	v_add_u32_e32 v1, s33, v119
	v_mad_u32_u24 v1, v1, s59, v117
	s_sub_i32 s20, s21, s20
	s_add_i32 s21, s2, 64
	s_and_b32 s26, s21, 0x1c0
	s_add_i32 s21, s2, 0x80
	s_and_b32 s22, s21, 0x1c0
	s_addk_i32 s2, 0xc0
	s_and_b32 s2, s2, 0x1c0
	s_mul_i32 s20, s20, 31
	s_ashr_i32 s21, s20, 31
	s_lshl_b64 s[20:21], s[20:21], 2
	s_add_u32 s20, s36, s20
	s_addc_u32 s21, s23, s21
	global_load_dword v194, v99, s[20:21] offset:868
	global_load_dword v195, v98, s[20:21] offset:868
	global_load_dword v196, v96, s[20:21] offset:868
	global_load_dword v197, v97, s[20:21] offset:868
	global_load_dword v198, v93, s[20:21] offset:868
	global_load_dword v199, v94, s[20:21] offset:868
	global_load_dword v200, v95, s[20:21] offset:868
	global_load_dword v201, v92, s[20:21] offset:868
	global_load_dword v202, v99, s[20:21] offset:992
	global_load_dword v203, v96, s[20:21] offset:992
	global_load_dword v204, v98, s[20:21] offset:992
	global_load_dword v205, v94, s[20:21] offset:992
	global_load_dword v206, v97, s[20:21] offset:992
	global_load_dword v207, v93, s[20:21] offset:992
	global_load_dword v208, v95, s[20:21] offset:992
	global_load_dword v209, v92, s[20:21] offset:992
	global_load_dword v210, v99, s[20:21] offset:1116
	global_load_dword v211, v96, s[20:21] offset:1116
	global_load_dword v212, v98, s[20:21] offset:1116
	global_load_dword v213, v94, s[20:21] offset:1116
	global_load_dword v226, v97, s[20:21] offset:1116
	global_load_dword v227, v93, s[20:21] offset:1116
	global_load_dword v228, v95, s[20:21] offset:1116
	global_load_dword v229, v92, s[20:21] offset:1116
	global_load_dword v230, v99, s[20:21] offset:1240
	global_load_dword v231, v96, s[20:21] offset:1240
	global_load_dword v232, v98, s[20:21] offset:1240
	global_load_dword v233, v97, s[20:21] offset:1240
	global_load_dword v234, v93, s[20:21] offset:1240
	global_load_dword v235, v94, s[20:21] offset:1240
	global_load_dword v236, v95, s[20:21] offset:1240
	global_load_dword v237, v92, s[20:21] offset:1240
	v_readlane_b32 s0, v255, 10
	v_readlane_b32 s1, v255, 11
	s_waitcnt vmcnt(33) lgkmcnt(1)
	v_mfma_f32_16x16x32_bf16 v[60:63], v[60:63], v[22:25], 0
	s_waitcnt vmcnt(32) lgkmcnt(0)
	v_mfma_f32_16x16x32_bf16 v[84:87], v[64:67], v[102:105], v[60:63]
	s_nop 5
	ds_read_b128 v[60:63], v1
	ds_read_b128 v[64:67], v1 offset:64
	v_add_u32_e32 v1, s26, v115
	s_waitcnt lgkmcnt(1)
	v_mfma_f32_16x16x32_bf16 v[60:63], v[60:63], v[22:25], 0
	v_mad_u32_u24 v1, v1, s59, v117
	s_waitcnt lgkmcnt(0)
	v_mfma_f32_16x16x32_bf16 v[76:79], v[64:67], v[102:105], v[60:63]
	s_nop 4
	ds_read_b128 v[60:63], v1
	ds_read_b128 v[64:67], v1 offset:64
	v_add_u32_e32 v1, s26, v119
	v_mad_u32_u24 v1, v1, s59, v117
	s_waitcnt lgkmcnt(1)
	v_mfma_f32_16x16x32_bf16 v[60:63], v[60:63], v[22:25], 0
	s_waitcnt lgkmcnt(0)
	v_mfma_f32_16x16x32_bf16 v[80:83], v[64:67], v[102:105], v[60:63]
	s_nop 5
	ds_read_b128 v[60:63], v1
	ds_read_b128 v[64:67], v1 offset:64
	v_add_u32_e32 v1, s22, v115
	s_waitcnt lgkmcnt(1)
	v_mfma_f32_16x16x32_bf16 v[60:63], v[60:63], v[22:25], 0
	v_mad_u32_u24 v1, v1, s59, v117
	s_waitcnt lgkmcnt(0)
	v_mfma_f32_16x16x32_bf16 v[68:71], v[64:67], v[102:105], v[60:63]
	s_nop 4
	ds_read_b128 v[60:63], v1
	ds_read_b128 v[64:67], v1 offset:64
	v_add_u32_e32 v1, s22, v119
	v_mad_u32_u24 v1, v1, s59, v117
	s_waitcnt lgkmcnt(1)
	v_mfma_f32_16x16x32_bf16 v[60:63], v[60:63], v[22:25], 0
	s_waitcnt lgkmcnt(0)
	v_mfma_f32_16x16x32_bf16 v[72:75], v[64:67], v[102:105], v[60:63]
	s_nop 5
	ds_read_b128 v[60:63], v1
	ds_read_b128 v[64:67], v1 offset:64
	v_add_u32_e32 v1, s2, v115
	s_waitcnt lgkmcnt(1)
	v_mfma_f32_16x16x32_bf16 v[60:63], v[60:63], v[22:25], 0
	v_mad_u32_u24 v1, v1, s59, v117
	s_waitcnt lgkmcnt(0)
	v_mfma_f32_16x16x32_bf16 v[60:63], v[64:67], v[102:105], v[60:63]
	ds_read_b128 v[64:67], v1
	ds_read_b128 v[158:161], v1 offset:64
	v_add_u32_e32 v1, s2, v119
	v_mad_u32_u24 v1, v1, s59, v117
	s_waitcnt lgkmcnt(1)
	v_mfma_f32_16x16x32_bf16 v[64:67], v[64:67], v[22:25], 0
	s_or_b32 s2, s2, s60
	s_waitcnt lgkmcnt(0)
	v_mfma_f32_16x16x32_bf16 v[64:67], v[158:161], v[102:105], v[64:67]
	ds_read_b128 v[158:161], v1
	ds_read_b128 v[162:165], v1 offset:64
	s_waitcnt lgkmcnt(1)
	v_mfma_f32_16x16x32_bf16 v[22:25], v[158:161], v[22:25], 0
	s_waitcnt vmcnt(0)
	v_fmamk_f32 v1, v194, 0x3fb8aa3b, v84
	s_waitcnt lgkmcnt(0)
	v_mfma_f32_16x16x32_bf16 v[22:25], v[162:165], v[102:105], v[22:25]
	v_cndmask_b32_e64 v1, v220, v1, s[38:39]
	v_fmamk_f32 v76, v197, 0x3fb8aa3b, v76
	v_fmamk_f32 v3, v195, 0x3fb8aa3b, v86
	v_cndmask_b32_e64 v59, v220, v3, s[42:43]
	v_cndmask_b32_e64 v76, v220, v76, s[46:47]
	v_fmamk_f32 v77, v198, 0x3fb8aa3b, v77
	v_cndmask_b32_e64 v77, v220, v77, s[48:49]
	v_fmamk_f32 v78, v200, 0x3fb8aa3b, v78
	v_cndmask_b32_e64 v84, v220, v78, s[50:51]
	v_fmac_f32_e32 v87, 0x3fb8aa3b, v199
	v_cndmask_b32_e64 v3, v220, v87, s[44:45]
	v_fmac_f32_e32 v79, 0x3fb8aa3b, v201
	v_cndmask_b32_e64 v78, v220, v79, s[52:53]
	v_fmamk_f32 v79, v202, 0x3fb8aa3b, v80
	v_cndmask_b32_e64 v79, v220, v79, s[38:39]
	v_fmamk_f32 v80, v203, 0x3fb8aa3b, v81
	v_cndmask_b32_e64 v80, v220, v80, s[40:41]
	v_fmamk_f32 v81, v204, 0x3fb8aa3b, v82
	v_cndmask_b32_e64 v82, v220, v81, s[42:43]
	v_fmac_f32_e32 v83, 0x3fb8aa3b, v205
	v_cndmask_b32_e64 v81, v220, v83, s[44:45]
	v_fmamk_f32 v68, v206, 0x3fb8aa3b, v68
	v_cndmask_b32_e64 v68, v220, v68, s[46:47]
	v_fmamk_f32 v69, v207, 0x3fb8aa3b, v69
	v_cndmask_b32_e64 v69, v220, v69, s[48:49]
	v_fmamk_f32 v70, v208, 0x3fb8aa3b, v70
	v_cndmask_b32_e64 v83, v220, v70, s[50:51]
	v_fmamk_f32 v2, v196, 0x3fb8aa3b, v85
	v_cndmask_b32_e64 v2, v220, v2, s[40:41]
	v_fmac_f32_e32 v71, 0x3fb8aa3b, v209
	v_cndmask_b32_e64 v70, v220, v71, s[52:53]
	v_max_f32_e32 v86, v83, v70
	v_max3_f32 v86, v68, v69, v86
	v_fmamk_f32 v71, v210, 0x3fb8aa3b, v72
	v_cndmask_b32_e64 v71, v220, v71, s[38:39]
	v_fmamk_f32 v72, v211, 0x3fb8aa3b, v73
	v_cndmask_b32_e64 v72, v220, v72, s[40:41]
	v_fmamk_f32 v73, v212, 0x3fb8aa3b, v74
	v_cndmask_b32_e64 v74, v220, v73, s[42:43]
	v_fmac_f32_e32 v75, 0x3fb8aa3b, v213
	v_cndmask_b32_e64 v73, v220, v75, s[44:45]
	v_fmamk_f32 v60, v226, 0x3fb8aa3b, v60
	v_cndmask_b32_e64 v60, v220, v60, s[46:47]
	v_fmamk_f32 v61, v227, 0x3fb8aa3b, v61
	v_cndmask_b32_e64 v75, v220, v61, s[48:49]
	v_fmamk_f32 v61, v228, 0x3fb8aa3b, v62
	v_cndmask_b32_e64 v85, v220, v61, s[50:51]
	v_fmac_f32_e32 v63, 0x3fb8aa3b, v229
	v_cndmask_b32_e64 v62, v220, v63, s[52:53]
	v_fmamk_f32 v61, v230, 0x3fb8aa3b, v64
	v_cndmask_b32_e64 v61, v220, v61, s[38:39]
	v_fmamk_f32 v64, v232, 0x3fb8aa3b, v66
	v_cndmask_b32_e64 v64, v220, v64, s[42:43]
	v_fmamk_f32 v22, v233, 0x3fb8aa3b, v22
	v_fmamk_f32 v63, v231, 0x3fb8aa3b, v65
	v_cndmask_b32_e64 v63, v220, v63, s[40:41]
	v_cndmask_b32_e64 v22, v220, v22, s[46:47]
	v_fmamk_f32 v23, v234, 0x3fb8aa3b, v23
	v_cndmask_b32_e64 v23, v220, v23, s[48:49]
	v_fmamk_f32 v24, v236, 0x3fb8aa3b, v24
	v_fmac_f32_e32 v67, 0x3fb8aa3b, v235
	v_cndmask_b32_e64 v65, v220, v67, s[44:45]
	v_max_f32_e32 v67, v84, v78
	v_max3_f32 v67, v76, v77, v67
	s_mov_b32 s20, 0xf149f2ca
	v_cndmask_b32_e64 v24, v220, v24, s[50:51]
	v_fmac_f32_e32 v25, 0x3fb8aa3b, v237
	v_max_f32_e32 v66, v59, v3
	v_max3_f32 v66, v1, v2, v66
	v_max3_f32 v66, v66, s20, v67
	v_max_f32_e32 v67, v82, v81
	v_max3_f32 v67, v79, v80, v67
	v_max3_f32 v66, v66, v67, v86
	v_max_f32_e32 v67, v74, v73
	v_max_f32_e32 v86, v85, v62
	v_cndmask_b32_e64 v25, v220, v25, s[52:53]
	v_max3_f32 v67, v71, v72, v67
	v_max3_f32 v86, v60, v75, v86
	v_max3_f32 v66, v66, v67, v86
	v_max_f32_e32 v67, v64, v65
	v_max_f32_e32 v86, v24, v25
	v_max3_f32 v67, v61, v63, v67
	v_max3_f32 v86, v22, v23, v86
	v_max3_f32 v66, v66, v67, v86
	ds_bpermute_b32 v67, v145, v66
	s_waitcnt lgkmcnt(0)
	v_max_f32_e32 v67, v67, v67
	v_max_f32_e32 v66, v66, v67
	ds_bpermute_b32 v67, v149, v66
	s_waitcnt lgkmcnt(0)
	v_max3_f32 v159, v66, v67, s20
	v_sub_f32_e32 v1, v1, v159
	v_exp_f32_e32 v67, v1
	v_sub_f32_e32 v2, v2, v159
	v_exp_f32_e32 v2, v2
	v_sub_f32_e32 v59, v59, v159
	v_exp_f32_e32 v59, v59
	v_sub_f32_e32 v3, v3, v159
	v_exp_f32_e32 v3, v3
	v_sub_f32_e32 v76, v76, v159
	v_add_f32_e32 v1, 0, v67
	v_exp_f32_e32 v76, v76
	v_sub_f32_e32 v77, v77, v159
	v_add_f32_e32 v1, v2, v1
	v_exp_f32_e32 v77, v77
	v_sub_f32_e32 v84, v84, v159
	v_add_f32_e32 v1, v59, v1
	v_exp_f32_e32 v84, v84
	v_sub_f32_e32 v78, v78, v159
	v_add_f32_e32 v1, v3, v1
	v_exp_f32_e32 v78, v78
	v_sub_f32_e32 v79, v79, v159
	v_add_f32_e32 v1, v76, v1
	v_exp_f32_e32 v86, v79
	v_sub_f32_e32 v79, v80, v159
	v_add_f32_e32 v1, v77, v1
	v_exp_f32_e32 v80, v79
	v_sub_f32_e32 v79, v82, v159
	v_add_f32_e32 v1, v84, v1
	v_exp_f32_e32 v82, v79
	v_sub_f32_e32 v79, v81, v159
	v_add_f32_e32 v1, v78, v1
	v_exp_f32_e32 v81, v79
	v_sub_f32_e32 v68, v68, v159
	v_add_f32_e32 v1, v86, v1
	v_exp_f32_e32 v87, v68
	v_sub_f32_e32 v68, v69, v159
	v_add_f32_e32 v1, v80, v1
	v_exp_f32_e32 v92, v68
	v_sub_f32_e32 v68, v83, v159
	v_add_f32_e32 v1, v82, v1
	v_exp_f32_e32 v83, v68
	v_sub_f32_e32 v68, v70, v159
	v_add_f32_e32 v1, v81, v1
	v_exp_f32_e32 v93, v68
	v_sub_f32_e32 v68, v71, v159
	v_add_f32_e32 v1, v87, v1
	v_exp_f32_e32 v94, v68
	v_sub_f32_e32 v68, v72, v159
	v_add_f32_e32 v1, v92, v1
	v_exp_f32_e32 v95, v68
	v_sub_f32_e32 v68, v74, v159
	v_add_f32_e32 v1, v83, v1
	v_exp_f32_e32 v96, v68
	v_sub_f32_e32 v68, v73, v159
	v_add_f32_e32 v1, v93, v1
	v_exp_f32_e32 v97, v68
	v_sub_f32_e32 v60, v60, v159
	v_add_f32_e32 v1, v94, v1
	v_exp_f32_e32 v98, v60
	v_sub_f32_e32 v60, v75, v159
	v_add_f32_e32 v1, v95, v1
	v_exp_f32_e32 v99, v60
	v_sub_f32_e32 v60, v85, v159
	v_add_f32_e32 v1, v96, v1
	v_exp_f32_e32 v85, v60
	v_sub_f32_e32 v60, v62, v159
	v_add_f32_e32 v1, v97, v1
	v_exp_f32_e32 v101, v60
	v_sub_f32_e32 v60, v61, v159
	v_add_f32_e32 v1, v98, v1
	v_exp_f32_e32 v102, v60
	v_sub_f32_e32 v60, v63, v159
	v_add_f32_e32 v1, v99, v1
	v_exp_f32_e32 v103, v60
	v_sub_f32_e32 v60, v64, v159
	v_add_f32_e32 v1, v85, v1
	v_exp_f32_e32 v104, v60
	v_sub_f32_e32 v60, v65, v159
	v_add_f32_e32 v1, v101, v1
	v_exp_f32_e32 v105, v60
	v_sub_f32_e32 v22, v22, v159
	v_add_f32_e32 v1, v102, v1
	v_exp_f32_e32 v106, v22
	v_sub_f32_e32 v22, v23, v159
	v_add_f32_e32 v1, v103, v1
	v_exp_f32_e32 v107, v22
	v_sub_f32_e32 v22, v24, v159
	s_or_b32 s20, s33, s60
	v_add_f32_e32 v1, v104, v1
	v_exp_f32_e32 v147, v22
	v_sub_f32_e32 v22, v25, v159
	v_cvt_pk_bf16_f32 v60, v67, v2
	v_lshl_add_u32 v2, s20, 1, v121
	v_sub_f32_e32 v66, 0xf149f2ca, v159
	v_add_f32_e32 v1, v105, v1
	v_exp_f32_e32 v148, v22
	v_cvt_pk_bf16_f32 v61, v59, v3
	v_add_u32_e32 v3, v2, v123
	v_add_f32_e32 v1, v106, v1
	v_exp_f32_e32 v22, v66
	v_cvt_pk_bf16_f32 v62, v76, v77
	v_cvt_pk_bf16_f32 v63, v84, v78
	ds_read2_b64 v[64:67], v3 offset1:4
	v_add_u32_e32 v59, 0x4000, v3
	v_add_u32_e32 v3, 0x8000, v3
	v_add_u32_e32 v2, v2, v125
	v_add_f32_e32 v1, v107, v1
	ds_read2_b64 v[68:71], v59 offset0:32 offset1:36
	ds_read2_b64 v[72:75], v3 offset0:64 offset1:68
	ds_read2_b64 v[76:79], v2 offset1:4
	v_add_f32_e32 v1, v147, v1
	v_add_f32_e32 v1, v148, v1
	ds_bpermute_b32 v23, v145, v1
	s_or_b32 s20, s26, s60
	v_mul_f32_e32 v22, 0, v22
	v_lshl_add_u32 v2, s20, 1, v121
	v_mov_b32_e32 v24, v22
	s_waitcnt lgkmcnt(0)
	v_add_f32_e32 v1, v1, v23
	v_mov_b32_e32 v23, v22
	v_mov_b32_e32 v25, v22
	v_add_u32_e32 v3, v2, v123
	v_add_u32_e32 v2, v2, v125
	v_mfma_f32_16x16x32_bf16 v[64:67], v[64:67], v[60:63], v[22:25]
	s_or_b32 s20, s22, s60
	ds_bpermute_b32 v158, v149, v1
	v_mfma_f32_16x16x32_bf16 v[68:71], v[68:71], v[60:63], v[22:25]
	v_mfma_f32_16x16x32_bf16 v[72:75], v[72:75], v[60:63], v[22:25]
	v_mfma_f32_16x16x32_bf16 v[60:63], v[76:79], v[60:63], v[22:25]
	v_cvt_pk_bf16_f32 v76, v86, v80
	v_cvt_pk_bf16_f32 v77, v82, v81
	v_cvt_pk_bf16_f32 v78, v87, v92
	v_cvt_pk_bf16_f32 v79, v83, v93
	ds_read2_b64 v[80:83], v3 offset1:4
	s_nop 1
	v_add_u32_e32 v23, 0x4000, v3
	s_waitcnt lgkmcnt(0)
	v_mfma_f32_16x16x32_bf16 v[64:67], v[80:83], v[76:79], v[64:67]
	ds_read2_b64 v[80:83], v23 offset0:32 offset1:36
	v_add_u32_e32 v3, 0x8000, v3
	s_waitcnt lgkmcnt(0)
	v_mfma_f32_16x16x32_bf16 v[68:71], v[80:83], v[76:79], v[68:71]
	ds_read2_b64 v[80:83], v3 offset0:64 offset1:68
	s_waitcnt lgkmcnt(0)
	v_mfma_f32_16x16x32_bf16 v[72:75], v[80:83], v[76:79], v[72:75]
	ds_read2_b64 v[80:83], v2 offset1:4
	v_lshl_add_u32 v2, s20, 1, v121
	v_add_u32_e32 v3, v2, v123
	s_waitcnt lgkmcnt(0)
	v_mfma_f32_16x16x32_bf16 v[60:63], v[80:83], v[76:79], v[60:63]
	v_cvt_pk_bf16_f32 v76, v94, v95
	v_cvt_pk_bf16_f32 v77, v96, v97
	v_cvt_pk_bf16_f32 v78, v98, v99
	v_cvt_pk_bf16_f32 v79, v85, v101
	ds_read2_b64 v[80:83], v3 offset1:4
	v_add_u32_e32 v23, 0x4000, v3
	s_waitcnt lgkmcnt(0)
	v_mfma_f32_16x16x32_bf16 v[64:67], v[80:83], v[76:79], v[64:67]
	ds_read2_b64 v[80:83], v23 offset0:32 offset1:36
	v_add_u32_e32 v3, 0x8000, v3
	v_add_u32_e32 v2, v2, v125
	s_waitcnt lgkmcnt(0)
	v_mfma_f32_16x16x32_bf16 v[68:71], v[80:83], v[76:79], v[68:71]
	ds_read2_b64 v[80:83], v3 offset0:64 offset1:68
	s_waitcnt lgkmcnt(0)
	v_mfma_f32_16x16x32_bf16 v[72:75], v[80:83], v[76:79], v[72:75]
	ds_read2_b64 v[80:83], v2 offset1:4
	v_lshl_add_u32 v2, s2, 1, v121
	v_add_u32_e32 v3, v2, v123
	s_waitcnt lgkmcnt(0)
	v_mfma_f32_16x16x32_bf16 v[76:79], v[80:83], v[76:79], v[60:63]
	v_cvt_pk_bf16_f32 v80, v102, v103
	v_cvt_pk_bf16_f32 v81, v104, v105
	v_cvt_pk_bf16_f32 v82, v106, v107
	v_cvt_pk_bf16_f32 v83, v147, v148
	s_nop 2
	ds_read2_b64 v[60:63], v3 offset1:4
	v_add_u32_e32 v23, 0x4000, v3
	s_waitcnt lgkmcnt(0)
	v_mfma_f32_16x16x32_bf16 v[60:63], v[60:63], v[80:83], v[64:67]
	s_nop 2
	ds_read2_b64 v[64:67], v23 offset0:32 offset1:36
	v_add_u32_e32 v3, 0x8000, v3
	v_add_u32_e32 v2, v2, v125
	s_waitcnt lgkmcnt(0)
	v_mfma_f32_16x16x32_bf16 v[64:67], v[64:67], v[80:83], v[68:71]
	s_nop 2
	ds_read2_b64 v[68:71], v3 offset0:64 offset1:68
	s_waitcnt lgkmcnt(0)
	v_mfma_f32_16x16x32_bf16 v[68:71], v[68:71], v[80:83], v[72:75]
	s_nop 2
	ds_read2_b64 v[72:75], v2 offset1:4
	s_waitcnt lgkmcnt(0)
	v_mfma_f32_16x16x32_bf16 v[72:75], v[72:75], v[80:83], v[76:79]
	s_barrier
	s_and_saveexec_b64 s[20:21], s[0:1]
	s_xor_b64 s[20:21], exec, s[20:21]
	s_cbranch_execz .LBB0_130
	s_lshl_b64 s[22:23], s[56:57], 15
	v_lshl_add_u64 v[2:3], v[130:131], 0, s[22:23]
	s_movk_i32 s2, 0x90
	s_movk_i32 s26, 0x5ff
	v_mov_b32_e32 v23, v192
	v_ashrrev_i32_e32 v24, 3, v23
	v_ashrrev_i32_e32 v25, 31, v24
	v_lshlrev_b64 v[176:177], 7, v[24:25]
	v_lshl_add_u64 v[176:177], v[2:3], 0, v[176:177]
	global_load_dwordx4 v[76:79], v[176:177], off
	v_mad_u32_u24 v168, v24, s2, v110
	v_add_u32_e32 v23, 0x200, v192
	v_ashrrev_i32_e32 v24, 3, v23
	v_ashrrev_i32_e32 v25, 31, v24
	v_lshlrev_b64 v[176:177], 7, v[24:25]
	v_lshl_add_u64 v[176:177], v[2:3], 0, v[176:177]
	global_load_dwordx4 v[80:83], v[176:177], off
	v_mad_u32_u24 v169, v24, s2, v110
	v_add_u32_e32 v23, 0x400, v192
	v_ashrrev_i32_e32 v24, 3, v23
	v_ashrrev_i32_e32 v25, 31, v24
	v_lshlrev_b64 v[176:177], 7, v[24:25]
	v_lshl_add_u64 v[176:177], v[2:3], 0, v[176:177]
	global_load_dwordx4 v[84:87], v[176:177], off
	v_mad_u32_u24 v170, v24, s2, v110
	v_add_u32_e32 v23, 0x600, v192
	v_ashrrev_i32_e32 v24, 3, v23
	v_ashrrev_i32_e32 v25, 31, v24
	v_lshlrev_b64 v[176:177], 7, v[24:25]
	v_lshl_add_u64 v[176:177], v[2:3], 0, v[176:177]
	global_load_dwordx4 v[92:95], v[176:177], off
	v_mad_u32_u24 v171, v24, s2, v110
	v_lshl_add_u64 v[2:3], v[132:133], 0, s[22:23]
	s_movk_i32 s2, 0x210
	v_mov_b32_e32 v23, v192
	v_ashrrev_i32_e32 v24, 5, v23
	v_ashrrev_i32_e32 v25, 31, v24
	v_lshlrev_b64 v[176:177], 9, v[24:25]
	v_lshl_add_u64 v[176:177], v[2:3], 0, v[176:177]
	global_load_dwordx4 v[96:99], v[176:177], off
	v_mad_u32_u24 v172, v24, s2, v134
	v_add_u32_e32 v23, 0x200, v192
	v_ashrrev_i32_e32 v24, 5, v23
	v_ashrrev_i32_e32 v25, 31, v24
	v_lshlrev_b64 v[176:177], 9, v[24:25]
	v_lshl_add_u64 v[176:177], v[2:3], 0, v[176:177]
	global_load_dwordx4 v[104:107], v[176:177], off
	v_mad_u32_u24 v173, v24, s2, v134
	v_add_u32_e32 v23, 0x400, v192
	v_ashrrev_i32_e32 v24, 5, v23
	v_ashrrev_i32_e32 v25, 31, v24
	v_lshlrev_b64 v[176:177], 9, v[24:25]
	v_lshl_add_u64 v[176:177], v[2:3], 0, v[176:177]
	global_load_dwordx4 v[160:163], v[176:177], off
	v_mad_u32_u24 v174, v24, s2, v134
	v_add_u32_e32 v23, 0x600, v192
	v_ashrrev_i32_e32 v24, 5, v23
	v_ashrrev_i32_e32 v25, 31, v24
	v_lshlrev_b64 v[176:177], 9, v[24:25]
	v_lshl_add_u64 v[176:177], v[2:3], 0, v[176:177]
	global_load_dwordx4 v[164:167], v[176:177], off
	v_mad_u32_u24 v175, v24, s2, v134
	s_waitcnt vmcnt(7)
	ds_write_b128 v168, v[76:79]
	s_waitcnt vmcnt(6)
	ds_write_b128 v169, v[80:83]
	s_waitcnt vmcnt(5)
	ds_write_b128 v170, v[84:87]
	s_waitcnt vmcnt(4)
	ds_write_b128 v171, v[92:95]
	s_waitcnt vmcnt(3)
	ds_write_b128 v172, v[96:99]
	s_waitcnt vmcnt(2)
	ds_write_b128 v173, v[104:107]
	s_waitcnt vmcnt(1)
	ds_write_b128 v174, v[160:163]
	s_waitcnt vmcnt(0)
	ds_write_b128 v175, v[164:167]
